# P8 gate phase: 64-lane sum via DPP row ops + readlane instead of 6 ds_bpermute round trips
# baseline (speedup 1.0000x reference)
.LBB0_776:
	v_lshlrev_b32_e32 v20, 16, v6
	v_mul_f32_e32 v21, 0xbfb8aa3b, v20
	v_and_b32_e32 v6, 0xffff0000, v6
	v_exp_f32_e32 v22, v21
	v_lshlrev_b32_e32 v21, 16, v7
	v_mul_f32_e32 v23, 0xbfb8aa3b, v6
	v_exp_f32_e32 v23, v23
	v_mul_f32_e32 v24, 0xbfb8aa3b, v21
	v_exp_f32_e32 v25, v24
	v_and_b32_e32 v7, 0xffff0000, v7
	v_add_f32_e32 v23, 1.0, v23
	v_add_f32_e32 v22, 1.0, v22
	v_rcp_f32_e32 v24, v23
	v_add_f32_e32 v23, 1.0, v25
	v_mul_f32_e32 v25, 0xbfb8aa3b, v7
	v_rcp_f32_e32 v22, v22
	v_rcp_f32_e32 v23, v23
	v_exp_f32_e32 v25, v25
	s_waitcnt vmcnt(0) lgkmcnt(0)
	v_lshlrev_b32_e32 v27, 16, v15
	v_lshlrev_b32_e32 v26, 16, v14
	v_pk_mul_f32 v[20:21], v[22:23], v[20:21]
	v_add_f32_e32 v22, 1.0, v25
	v_rcp_f32_e32 v25, v22
	v_and_b32_e32 v15, 0xffff0000, v15
	v_and_b32_e32 v14, 0xffff0000, v14
	v_pk_mul_f32 v[20:21], v[20:21], v[26:27]
	v_pk_mul_f32 v[6:7], v[24:25], v[6:7]
	v_lshlrev_b32_e32 v29, 16, v17
	v_pk_mul_f32 v[6:7], v[6:7], v[14:15]
	v_lshlrev_b32_e32 v14, 16, v8
	v_mul_f32_e32 v15, 0xbfb8aa3b, v14
	v_and_b32_e32 v8, 0xffff0000, v8
	v_exp_f32_e32 v24, v15
	v_lshlrev_b32_e32 v15, 16, v9
	v_mul_f32_e32 v25, 0xbfb8aa3b, v8
	v_exp_f32_e32 v25, v25
	v_mul_f32_e32 v26, 0xbfb8aa3b, v15
	v_exp_f32_e32 v27, v26
	v_and_b32_e32 v9, 0xffff0000, v9
	v_add_f32_e32 v25, 1.0, v25
	v_add_f32_e32 v24, 1.0, v24
	v_rcp_f32_e32 v26, v25
	v_add_f32_e32 v25, 1.0, v27
	v_mul_f32_e32 v27, 0xbfb8aa3b, v9
	v_rcp_f32_e32 v24, v24
	v_rcp_f32_e32 v25, v25
	v_exp_f32_e32 v27, v27
	v_lshlrev_b32_e32 v28, 16, v16
	v_and_b32_e32 v17, 0xffff0000, v17
	v_pk_mul_f32 v[14:15], v[24:25], v[14:15]
	v_add_f32_e32 v24, 1.0, v27
	v_rcp_f32_e32 v27, v24
	v_and_b32_e32 v16, 0xffff0000, v16
	v_pk_mul_f32 v[14:15], v[14:15], v[28:29]
	v_lshlrev_b32_e32 v31, 16, v11
	v_pk_mul_f32 v[8:9], v[26:27], v[8:9]
	v_lshlrev_b32_e32 v30, 16, v10
	v_pk_mul_f32 v[8:9], v[8:9], v[16:17]
	v_lshlrev_b32_e32 v16, 16, v2
	v_mul_f32_e32 v17, 0xbfb8aa3b, v16
	v_and_b32_e32 v2, 0xffff0000, v2
	v_exp_f32_e32 v26, v17
	v_lshlrev_b32_e32 v17, 16, v3
	v_mul_f32_e32 v27, 0xbfb8aa3b, v2
	v_exp_f32_e32 v27, v27
	v_mul_f32_e32 v28, 0xbfb8aa3b, v17
	v_exp_f32_e32 v29, v28
	v_and_b32_e32 v3, 0xffff0000, v3
	v_add_f32_e32 v27, 1.0, v27
	v_add_f32_e32 v26, 1.0, v26
	v_rcp_f32_e32 v28, v27
	v_add_f32_e32 v27, 1.0, v29
	v_mul_f32_e32 v29, 0xbfb8aa3b, v3
	v_rcp_f32_e32 v26, v26
	v_rcp_f32_e32 v27, v27
	v_exp_f32_e32 v29, v29
	v_and_b32_e32 v11, 0xffff0000, v11
	v_and_b32_e32 v10, 0xffff0000, v10
	v_pk_mul_f32 v[16:17], v[26:27], v[16:17]
	v_add_f32_e32 v26, 1.0, v29
	v_rcp_f32_e32 v29, v26
	v_pk_mul_f32 v[16:17], v[16:17], v[30:31]
	v_pk_mul_f32 v[22:23], v[6:7], v[6:7]
	v_lshlrev_b32_e32 v33, 16, v13
	v_pk_mul_f32 v[2:3], v[28:29], v[2:3]
	v_lshlrev_b32_e32 v32, 16, v12
	v_pk_mul_f32 v[10:11], v[2:3], v[10:11]
	v_lshlrev_b32_e32 v2, 16, v4
	v_mul_f32_e32 v3, 0xbfb8aa3b, v2
	v_and_b32_e32 v4, 0xffff0000, v4
	v_exp_f32_e32 v28, v3
	v_lshlrev_b32_e32 v3, 16, v5
	v_mul_f32_e32 v29, 0xbfb8aa3b, v4
	v_exp_f32_e32 v29, v29
	v_mul_f32_e32 v30, 0xbfb8aa3b, v3
	v_exp_f32_e32 v31, v30
	v_and_b32_e32 v5, 0xffff0000, v5
	v_add_f32_e32 v29, 1.0, v29
	v_add_f32_e32 v28, 1.0, v28
	v_rcp_f32_e32 v30, v29
	v_add_f32_e32 v29, 1.0, v31
	v_mul_f32_e32 v31, 0xbfb8aa3b, v5
	v_rcp_f32_e32 v28, v28
	v_rcp_f32_e32 v29, v29
	v_exp_f32_e32 v31, v31
	v_pk_fma_f32 v[22:23], v[20:21], v[20:21], v[22:23]
	v_pk_mul_f32 v[24:25], v[8:9], v[8:9]
	v_pk_mul_f32 v[2:3], v[28:29], v[2:3]
	v_add_f32_e32 v28, 1.0, v31
	v_rcp_f32_e32 v31, v28
	v_pk_mul_f32 v[28:29], v[2:3], v[32:33]
	v_and_b32_e32 v3, 0xffff0000, v13
	v_and_b32_e32 v2, 0xffff0000, v12
	v_pk_mul_f32 v[4:5], v[30:31], v[4:5]
	v_pk_fma_f32 v[24:25], v[14:15], v[14:15], v[24:25]
	v_pk_mul_f32 v[12:13], v[4:5], v[2:3]
	v_add_f32_e32 v4, v22, v23
	v_pk_mul_f32 v[26:27], v[10:11], v[10:11]
	v_add_f32_e32 v4, v24, v4
	v_pk_fma_f32 v[26:27], v[16:17], v[16:17], v[26:27]
	v_add_f32_e32 v4, v25, v4
	v_pk_mul_f32 v[2:3], v[12:13], v[12:13]
	v_add_f32_e32 v4, v4, v26
	v_pk_fma_f32 v[2:3], v[28:29], v[28:29], v[2:3]
	v_add_f32_e32 v4, v27, v4
	v_add_f32_e32 v2, v2, v4
	v_add_f32_e32 v2, v3, v2
	s_add_i32 s25, s25, s28
	s_add_i32 s19, s19, s20
	s_cmpk_lt_i32 s25, 0x400
	s_nop 1
	v_add_f32_dpp v2, v2, v2 quad_perm:[1,0,3,2] row_mask:0xf bank_mask:0xf
	s_nop 1
	v_add_f32_dpp v2, v2, v2 quad_perm:[2,3,0,1] row_mask:0xf bank_mask:0xf
	s_nop 1
	v_add_f32_dpp v2, v2, v2 row_half_mirror row_mask:0xf bank_mask:0xf
	s_nop 1
	v_add_f32_dpp v2, v2, v2 row_mirror row_mask:0xf bank_mask:0xf
	s_nop 0
	v_readlane_b32 s98, v2, 0
	v_readlane_b32 s99, v2, 16
	v_readlane_b32 s100, v2, 32
	v_readlane_b32 s101, v2, 48
	v_mov_b32_e32 v3, s98
	v_add_f32_e32 v3, s99, v3
	v_add_f32_e32 v3, s100, v3
	v_add_f32_e32 v2, s101, v3
	s_waitcnt lgkmcnt(0)
	v_fmamk_f32 v2, v2, 0x3a800000, v138
	v_mul_f32_e32 v3, 0x4b800000, v2
	v_cmp_gt_f32_e32 vcc, s23, v2
	s_nop 1
	v_cndmask_b32_e32 v2, v2, v3, vcc
	v_rsq_f32_e32 v4, v2
	v_lshlrev_b64 v[2:3], 12, v[18:19]
	v_lshl_add_u64 v[2:3], s[10:11], 0, v[2:3]
	v_lshl_add_u64 v[18:19], v[2:3], 0, v[74:75]
	v_mul_f32_e32 v2, 0x45800000, v4
	v_cndmask_b32_e32 v22, v4, v2, vcc
	v_pk_mul_f32 v[4:5], v[6:7], v[22:23] op_sel_hi:[1,0]
	v_pk_mul_f32 v[8:9], v[8:9], v[22:23] op_sel_hi:[1,0]
	v_pk_mul_f32 v[2:3], v[20:21], v[22:23] op_sel_hi:[1,0]
	v_pk_mul_f32 v[6:7], v[14:15], v[22:23] op_sel_hi:[1,0]
	v_bfe_u32 v14, v9, 16, 1
	v_bfe_u32 v15, v8, 16, 1
	v_bfe_u32 v20, v5, 16, 1
	v_bfe_u32 v21, v4, 16, 1
	v_add3_u32 v21, v4, v21, s24
	v_add3_u32 v20, v5, v20, s24
	v_add3_u32 v4, v8, v15, s24
	v_add3_u32 v5, v9, v14, s24
	v_bfe_u32 v8, v2, 16, 1
	v_bfe_u32 v9, v3, 16, 1
	v_bfe_u32 v14, v6, 16, 1
	v_bfe_u32 v15, v7, 16, 1
	v_add3_u32 v7, v7, v15, s24
	v_add3_u32 v6, v6, v14, s24
	v_add3_u32 v3, v3, v9, s24
	v_add3_u32 v2, v2, v8, s24
	v_lshrrev_b32_e32 v2, 16, v2
	v_lshrrev_b32_e32 v3, 16, v3
	v_lshrrev_b32_e32 v6, 16, v6
	v_lshrrev_b32_e32 v7, 16, v7
	v_and_or_b32 v5, v5, s22, v7
	v_and_or_b32 v4, v4, s22, v6
	v_and_or_b32 v3, v20, s22, v3
	v_and_or_b32 v2, v21, s22, v2
	global_store_dwordx4 v[18:19], v[2:5], off
	v_pk_mul_f32 v[8:9], v[12:13], v[22:23] op_sel_hi:[1,0]
	v_pk_mul_f32 v[6:7], v[28:29], v[22:23] op_sel_hi:[1,0]
	v_pk_mul_f32 v[4:5], v[10:11], v[22:23] op_sel_hi:[1,0]
	v_pk_mul_f32 v[2:3], v[16:17], v[22:23] op_sel_hi:[1,0]
	v_bfe_u32 v10, v9, 16, 1
	v_bfe_u32 v11, v8, 16, 1
	v_bfe_u32 v12, v5, 16, 1
	v_bfe_u32 v13, v4, 16, 1
	v_add3_u32 v13, v4, v13, s24
	v_add3_u32 v12, v5, v12, s24
	v_add3_u32 v4, v8, v11, s24
	v_add3_u32 v5, v9, v10, s24
	v_bfe_u32 v8, v2, 16, 1
	v_bfe_u32 v9, v3, 16, 1
	v_bfe_u32 v10, v6, 16, 1
	v_bfe_u32 v11, v7, 16, 1
	v_add3_u32 v7, v7, v11, s24
	v_add3_u32 v6, v6, v10, s24
	v_add3_u32 v3, v3, v9, s24
	v_add3_u32 v2, v2, v8, s24
	v_lshrrev_b32_e32 v2, 16, v2
	v_lshrrev_b32_e32 v3, 16, v3
	v_lshrrev_b32_e32 v6, 16, v6
	v_lshrrev_b32_e32 v7, 16, v7
	v_and_or_b32 v5, v5, s22, v7
	v_and_or_b32 v4, v4, s22, v6
	v_and_or_b32 v3, v12, s22, v3
	v_and_or_b32 v2, v13, s22, v2
	global_store_dwordx4 v[18:19], v[2:5], off offset:1024
	s_barrier
	s_cbranch_scc0 .LBB0_843

.LBB0_787:
	s_waitcnt vmcnt(15)
	v_lshlrev_b32_e32 v98, 16, v62
	v_mul_f32_e32 v95, 0xbfb8aa3b, v98
	v_exp_f32_e32 v95, v95
	v_and_b32_e32 v62, 0xffff0000, v62
	v_lshlrev_b32_e32 v99, 16, v63
	v_mul_f32_e32 v139, 0xbfb8aa3b, v62
	v_add_f32_e32 v95, 1.0, v95
	v_rcp_f32_e32 v140, v95
	v_exp_f32_e32 v95, v139
	v_mul_f32_e32 v139, 0xbfb8aa3b, v99
	v_exp_f32_e32 v139, v139
	v_and_b32_e32 v63, 0xffff0000, v63
	v_add_f32_e32 v95, 1.0, v95
	v_rcp_f32_e32 v142, v95
	v_add_f32_e32 v95, 1.0, v139
	v_rcp_f32_e32 v141, v95
	v_mul_f32_e32 v95, 0xbfb8aa3b, v63
	v_exp_f32_e32 v95, v95
	s_waitcnt vmcnt(0) lgkmcnt(0)
	v_lshlrev_b32_e32 v145, 16, v71
	v_lshlrev_b32_e32 v144, 16, v70
	v_and_b32_e32 v71, 0xffff0000, v71
	v_add_f32_e32 v95, 1.0, v95
	v_rcp_f32_e32 v143, v95
	v_and_b32_e32 v70, 0xffff0000, v70
	v_pk_mul_f32 v[98:99], v[140:141], v[98:99]
	v_lshlrev_b32_e32 v149, 16, v73
	v_pk_mul_f32 v[62:63], v[142:143], v[62:63]
	v_pk_mul_f32 v[98:99], v[98:99], v[144:145]
	v_pk_mul_f32 v[62:63], v[62:63], v[70:71]
	v_lshlrev_b32_e32 v70, 16, v64
	v_mul_f32_e32 v71, 0xbfb8aa3b, v70
	v_exp_f32_e32 v95, v71
	v_and_b32_e32 v64, 0xffff0000, v64
	v_lshlrev_b32_e32 v71, 16, v65
	v_mul_f32_e32 v139, 0xbfb8aa3b, v71
	v_add_f32_e32 v95, 1.0, v95
	v_rcp_f32_e32 v142, v95
	v_mul_f32_e32 v95, 0xbfb8aa3b, v64
	v_exp_f32_e32 v95, v95
	v_exp_f32_e32 v139, v139
	v_and_b32_e32 v65, 0xffff0000, v65
	v_lshlrev_b32_e32 v148, 16, v72
	v_add_f32_e32 v95, 1.0, v95
	v_rcp_f32_e32 v144, v95
	v_add_f32_e32 v95, 1.0, v139
	v_rcp_f32_e32 v143, v95
	v_mul_f32_e32 v95, 0xbfb8aa3b, v65
	v_exp_f32_e32 v95, v95
	v_and_b32_e32 v73, 0xffff0000, v73
	v_and_b32_e32 v72, 0xffff0000, v72
	v_pk_mul_f32 v[70:71], v[142:143], v[70:71]
	v_add_f32_e32 v95, 1.0, v95
	v_rcp_f32_e32 v145, v95
	v_pk_mul_f32 v[70:71], v[70:71], v[148:149]
	v_lshlrev_b32_e32 v151, 16, v67
	v_lshlrev_b32_e32 v150, 16, v66
	v_pk_mul_f32 v[64:65], v[144:145], v[64:65]
	v_and_b32_e32 v67, 0xffff0000, v67
	v_pk_mul_f32 v[64:65], v[64:65], v[72:73]
	v_lshlrev_b32_e32 v72, 16, v58
	v_mul_f32_e32 v73, 0xbfb8aa3b, v72
	v_exp_f32_e32 v95, v73
	v_and_b32_e32 v58, 0xffff0000, v58
	v_lshlrev_b32_e32 v73, 16, v59
	v_mul_f32_e32 v139, 0xbfb8aa3b, v73
	v_add_f32_e32 v95, 1.0, v95
	v_rcp_f32_e32 v144, v95
	v_mul_f32_e32 v95, 0xbfb8aa3b, v58
	v_exp_f32_e32 v95, v95
	v_exp_f32_e32 v139, v139
	v_and_b32_e32 v59, 0xffff0000, v59
	v_and_b32_e32 v66, 0xffff0000, v66
	v_add_f32_e32 v95, 1.0, v95
	v_rcp_f32_e32 v148, v95
	v_add_f32_e32 v95, 1.0, v139
	v_rcp_f32_e32 v145, v95
	v_mul_f32_e32 v95, 0xbfb8aa3b, v59
	v_exp_f32_e32 v95, v95
	v_pk_mul_f32 v[140:141], v[62:63], v[62:63]
	v_pk_mul_f32 v[72:73], v[144:145], v[72:73]
	v_lshlrev_b32_e32 v153, 16, v69
	v_add_f32_e32 v95, 1.0, v95
	v_rcp_f32_e32 v149, v95
	v_pk_mul_f32 v[72:73], v[72:73], v[150:151]
	v_lshlrev_b32_e32 v152, 16, v68
	v_pk_fma_f32 v[140:141], v[98:99], v[98:99], v[140:141]
	v_pk_mul_f32 v[58:59], v[148:149], v[58:59]
	v_pk_mul_f32 v[142:143], v[64:65], v[64:65]
	v_pk_mul_f32 v[66:67], v[58:59], v[66:67]
	v_lshlrev_b32_e32 v58, 16, v60
	v_mul_f32_e32 v59, 0xbfb8aa3b, v58
	v_exp_f32_e32 v95, v59
	v_and_b32_e32 v60, 0xffff0000, v60
	v_lshlrev_b32_e32 v59, 16, v61
	v_mul_f32_e32 v139, 0xbfb8aa3b, v59
	v_add_f32_e32 v95, 1.0, v95
	v_rcp_f32_e32 v148, v95
	v_mul_f32_e32 v95, 0xbfb8aa3b, v60
	v_exp_f32_e32 v95, v95
	v_exp_f32_e32 v139, v139
	v_and_b32_e32 v61, 0xffff0000, v61
	v_pk_fma_f32 v[142:143], v[70:71], v[70:71], v[142:143]
	v_add_f32_e32 v95, 1.0, v95
	v_rcp_f32_e32 v150, v95
	v_add_f32_e32 v95, 1.0, v139
	v_rcp_f32_e32 v149, v95
	v_mul_f32_e32 v95, 0xbfb8aa3b, v61
	v_exp_f32_e32 v95, v95
	v_pk_mul_f32 v[144:145], v[66:67], v[66:67]
	v_pk_mul_f32 v[58:59], v[148:149], v[58:59]
	v_pk_fma_f32 v[144:145], v[72:73], v[72:73], v[144:145]
	v_add_f32_e32 v95, 1.0, v95
	v_rcp_f32_e32 v151, v95
	v_pk_mul_f32 v[148:149], v[58:59], v[152:153]
	v_and_b32_e32 v59, 0xffff0000, v69
	v_and_b32_e32 v58, 0xffff0000, v68
	v_pk_mul_f32 v[60:61], v[150:151], v[60:61]
	s_lshl_b32 s9, s26, 9
	v_pk_mul_f32 v[68:69], v[60:61], v[58:59]
	v_add_f32_e32 v60, v140, v141
	v_add_f32_e32 v60, v142, v60
	v_add_f32_e32 v60, v143, v60
	v_pk_mul_f32 v[58:59], v[68:69], v[68:69]
	v_add_f32_e32 v60, v60, v144
	v_pk_fma_f32 v[58:59], v[148:149], v[148:149], v[58:59]
	v_add_f32_e32 v60, v145, v60
	v_add_f32_e32 v58, v58, v60
	v_add_f32_e32 v58, v59, v58
	s_lshl_b32 s9, s9, 2
	s_add_u32 s10, s56, s9
	s_addc_u32 s11, s57, 0
	s_mov_b64 s[16:17], -1
	s_nop 1
	v_add_f32_dpp v58, v58, v58 quad_perm:[1,0,3,2] row_mask:0xf bank_mask:0xf
	s_nop 1
	v_add_f32_dpp v58, v58, v58 quad_perm:[2,3,0,1] row_mask:0xf bank_mask:0xf
	s_nop 1
	v_add_f32_dpp v58, v58, v58 row_half_mirror row_mask:0xf bank_mask:0xf
	s_nop 1
	v_add_f32_dpp v58, v58, v58 row_mirror row_mask:0xf bank_mask:0xf
	s_nop 0
	v_readlane_b32 s98, v58, 0
	v_readlane_b32 s99, v58, 16
	v_readlane_b32 s100, v58, 32
	v_readlane_b32 s101, v58, 48
	v_mov_b32_e32 v59, s98
	v_add_f32_e32 v59, s99, v59
	v_add_f32_e32 v59, s100, v59
	v_add_f32_e32 v58, s101, v59
	s_waitcnt lgkmcnt(0)
	v_fmamk_f32 v58, v58, 0x3a800000, v138
	v_mul_f32_e32 v59, 0x4b800000, v58
	v_cmp_gt_f32_e32 vcc, s23, v58
	s_nop 1
	v_cndmask_b32_e32 v58, v58, v59, vcc
	v_rsq_f32_e32 v60, v58
	v_lshl_add_u64 v[58:59], s[10:11], 0, v[96:97]
	v_lshl_add_u64 v[96:97], v[58:59], 0, v[74:75]
	v_mul_f32_e32 v58, 0x45800000, v60
	v_cndmask_b32_e32 v140, v60, v58, vcc
	v_pk_mul_f32 v[60:61], v[62:63], v[140:141] op_sel_hi:[1,0]
	v_pk_mul_f32 v[64:65], v[64:65], v[140:141] op_sel_hi:[1,0]
	v_pk_mul_f32 v[58:59], v[98:99], v[140:141] op_sel_hi:[1,0]
	v_pk_mul_f32 v[62:63], v[70:71], v[140:141] op_sel_hi:[1,0]
	v_bfe_u32 v70, v65, 16, 1
	v_bfe_u32 v71, v64, 16, 1
	v_bfe_u32 v95, v61, 16, 1
	v_bfe_u32 v98, v60, 16, 1
	v_add3_u32 v98, v60, v98, s24
	v_add3_u32 v95, v61, v95, s24
	v_add3_u32 v60, v64, v71, s24
	v_add3_u32 v61, v65, v70, s24
	v_bfe_u32 v64, v58, 16, 1
	v_bfe_u32 v65, v59, 16, 1
	v_bfe_u32 v70, v62, 16, 1
	v_bfe_u32 v71, v63, 16, 1
	v_add3_u32 v63, v63, v71, s24
	v_add3_u32 v62, v62, v70, s24
	v_add3_u32 v59, v59, v65, s24
	v_add3_u32 v58, v58, v64, s24
	v_lshrrev_b32_e32 v58, 16, v58
	v_lshrrev_b32_e32 v59, 16, v59
	v_lshrrev_b32_e32 v62, 16, v62
	v_lshrrev_b32_e32 v63, 16, v63
	v_and_or_b32 v61, v61, s22, v63
	v_and_or_b32 v60, v60, s22, v62
	v_and_or_b32 v59, v95, s22, v59
	v_and_or_b32 v58, v98, s22, v58
	global_store_dwordx4 v[96:97], v[58:61], off
	v_pk_mul_f32 v[64:65], v[68:69], v[140:141] op_sel_hi:[1,0]
	v_pk_mul_f32 v[62:63], v[148:149], v[140:141] op_sel_hi:[1,0]
	v_pk_mul_f32 v[60:61], v[66:67], v[140:141] op_sel_hi:[1,0]
	v_pk_mul_f32 v[58:59], v[72:73], v[140:141] op_sel_hi:[1,0]
	v_bfe_u32 v66, v65, 16, 1
	v_bfe_u32 v67, v64, 16, 1
	v_bfe_u32 v68, v61, 16, 1
	v_bfe_u32 v69, v60, 16, 1
	v_add3_u32 v69, v60, v69, s24
	v_add3_u32 v68, v61, v68, s24
	v_add3_u32 v60, v64, v67, s24
	v_add3_u32 v61, v65, v66, s24
	v_bfe_u32 v64, v58, 16, 1
	v_bfe_u32 v65, v59, 16, 1
	v_bfe_u32 v66, v62, 16, 1
	v_bfe_u32 v67, v63, 16, 1
	v_add3_u32 v63, v63, v67, s24
	v_add3_u32 v62, v62, v66, s24
	v_add3_u32 v59, v59, v65, s24
	v_add3_u32 v58, v58, v64, s24
	v_lshrrev_b32_e32 v58, 16, v58
	v_lshrrev_b32_e32 v59, 16, v59
	v_lshrrev_b32_e32 v62, 16, v62
	v_lshrrev_b32_e32 v63, 16, v63
	v_add_u32_e32 v66, s8, v124
	v_and_or_b32 v61, v61, s22, v63
	v_and_or_b32 v60, v60, s22, v62
	v_and_or_b32 v59, v68, s22, v59
	v_and_or_b32 v58, v69, s22, v58
	v_ashrrev_i32_e32 v67, 31, v66
	global_store_dwordx4 v[96:97], v[58:61], off offset:1024
	s_and_b64 vcc, exec, s[0:1]
	s_nop 0
	v_lshlrev_b64 v[58:59], 11, v[66:67]
	v_lshl_add_u64 v[68:69], s[6:7], 0, v[58:59]
	s_cbranch_vccnz .LBB0_791
	v_lshl_add_u64 v[58:59], v[68:69], 0, v[74:75]
	global_load_dwordx4 v[62:65], v[58:59], off nt
	s_cbranch_execz .LBB0_792

.LBB0_795:
	v_lshlrev_b32_e32 v68, 16, v54
	v_mul_f32_e32 v69, 0xbfb8aa3b, v68
	v_and_b32_e32 v54, 0xffff0000, v54
	v_exp_f32_e32 v70, v69
	v_lshlrev_b32_e32 v69, 16, v55
	v_mul_f32_e32 v71, 0xbfb8aa3b, v54
	v_exp_f32_e32 v71, v71
	v_mul_f32_e32 v72, 0xbfb8aa3b, v69
	v_exp_f32_e32 v73, v72
	v_and_b32_e32 v55, 0xffff0000, v55
	v_add_f32_e32 v71, 1.0, v71
	v_add_f32_e32 v70, 1.0, v70
	v_rcp_f32_e32 v72, v71
	v_add_f32_e32 v71, 1.0, v73
	v_mul_f32_e32 v73, 0xbfb8aa3b, v55
	v_rcp_f32_e32 v70, v70
	v_rcp_f32_e32 v71, v71
	v_exp_f32_e32 v73, v73
	s_waitcnt vmcnt(0) lgkmcnt(0)
	v_lshlrev_b32_e32 v97, 16, v63
	v_lshlrev_b32_e32 v96, 16, v62
	v_pk_mul_f32 v[68:69], v[70:71], v[68:69]
	v_add_f32_e32 v70, 1.0, v73
	v_rcp_f32_e32 v73, v70
	v_and_b32_e32 v63, 0xffff0000, v63
	v_and_b32_e32 v62, 0xffff0000, v62
	v_pk_mul_f32 v[68:69], v[68:69], v[96:97]
	v_pk_mul_f32 v[54:55], v[72:73], v[54:55]
	v_lshlrev_b32_e32 v99, 16, v65
	v_pk_mul_f32 v[54:55], v[54:55], v[62:63]
	v_lshlrev_b32_e32 v62, 16, v56
	v_mul_f32_e32 v63, 0xbfb8aa3b, v62
	v_and_b32_e32 v56, 0xffff0000, v56
	v_exp_f32_e32 v72, v63
	v_lshlrev_b32_e32 v63, 16, v57
	v_mul_f32_e32 v73, 0xbfb8aa3b, v56
	v_exp_f32_e32 v73, v73
	v_mul_f32_e32 v95, 0xbfb8aa3b, v63
	v_exp_f32_e32 v95, v95
	v_and_b32_e32 v57, 0xffff0000, v57
	v_add_f32_e32 v73, 1.0, v73
	v_add_f32_e32 v72, 1.0, v72
	v_rcp_f32_e32 v96, v73
	v_add_f32_e32 v73, 1.0, v95
	v_mul_f32_e32 v95, 0xbfb8aa3b, v57
	v_rcp_f32_e32 v72, v72
	v_rcp_f32_e32 v73, v73
	v_exp_f32_e32 v95, v95
	v_lshlrev_b32_e32 v98, 16, v64
	v_and_b32_e32 v65, 0xffff0000, v65
	v_pk_mul_f32 v[62:63], v[72:73], v[62:63]
	v_add_f32_e32 v72, 1.0, v95
	v_rcp_f32_e32 v97, v72
	v_and_b32_e32 v64, 0xffff0000, v64
	v_pk_mul_f32 v[62:63], v[62:63], v[98:99]
	v_lshlrev_b32_e32 v141, 16, v59
	v_pk_mul_f32 v[56:57], v[96:97], v[56:57]
	v_lshlrev_b32_e32 v140, 16, v58
	v_pk_mul_f32 v[56:57], v[56:57], v[64:65]
	v_lshlrev_b32_e32 v64, 16, v50
	v_mul_f32_e32 v65, 0xbfb8aa3b, v64
	v_exp_f32_e32 v95, v65
	v_and_b32_e32 v50, 0xffff0000, v50
	v_lshlrev_b32_e32 v65, 16, v51
	v_mul_f32_e32 v97, 0xbfb8aa3b, v65
	v_add_f32_e32 v95, 1.0, v95
	v_rcp_f32_e32 v96, v95
	v_mul_f32_e32 v95, 0xbfb8aa3b, v50
	v_exp_f32_e32 v95, v95
	v_exp_f32_e32 v97, v97
	v_and_b32_e32 v51, 0xffff0000, v51
	v_and_b32_e32 v59, 0xffff0000, v59
	v_add_f32_e32 v95, 1.0, v95
	v_rcp_f32_e32 v98, v95
	v_add_f32_e32 v95, 1.0, v97
	v_rcp_f32_e32 v97, v95
	v_mul_f32_e32 v95, 0xbfb8aa3b, v51
	v_exp_f32_e32 v95, v95
	v_and_b32_e32 v58, 0xffff0000, v58
	v_pk_mul_f32 v[64:65], v[96:97], v[64:65]
	v_pk_mul_f32 v[70:71], v[54:55], v[54:55]
	v_add_f32_e32 v95, 1.0, v95
	v_rcp_f32_e32 v99, v95
	v_pk_mul_f32 v[64:65], v[64:65], v[140:141]
	v_lshlrev_b32_e32 v143, 16, v61
	v_lshlrev_b32_e32 v142, 16, v60
	v_pk_mul_f32 v[50:51], v[98:99], v[50:51]
	v_pk_fma_f32 v[70:71], v[68:69], v[68:69], v[70:71]
	v_pk_mul_f32 v[58:59], v[50:51], v[58:59]
	v_lshlrev_b32_e32 v50, 16, v52
	v_mul_f32_e32 v51, 0xbfb8aa3b, v50
	v_exp_f32_e32 v95, v51
	v_and_b32_e32 v52, 0xffff0000, v52
	v_lshlrev_b32_e32 v51, 16, v53
	v_mul_f32_e32 v99, 0xbfb8aa3b, v51
	v_add_f32_e32 v95, 1.0, v95
	v_rcp_f32_e32 v98, v95
	v_mul_f32_e32 v95, 0xbfb8aa3b, v52
	v_exp_f32_e32 v95, v95
	v_exp_f32_e32 v99, v99
	v_and_b32_e32 v53, 0xffff0000, v53
	v_pk_mul_f32 v[72:73], v[56:57], v[56:57]
	v_add_f32_e32 v95, 1.0, v95
	v_rcp_f32_e32 v140, v95
	v_add_f32_e32 v95, 1.0, v99
	v_rcp_f32_e32 v99, v95
	v_mul_f32_e32 v95, 0xbfb8aa3b, v53
	v_exp_f32_e32 v95, v95
	v_pk_fma_f32 v[72:73], v[62:63], v[62:63], v[72:73]
	v_pk_mul_f32 v[50:51], v[98:99], v[50:51]
	v_pk_mul_f32 v[96:97], v[58:59], v[58:59]
	v_add_f32_e32 v95, 1.0, v95
	v_rcp_f32_e32 v141, v95
	v_pk_mul_f32 v[98:99], v[50:51], v[142:143]
	v_and_b32_e32 v51, 0xffff0000, v61
	v_and_b32_e32 v50, 0xffff0000, v60
	v_pk_mul_f32 v[52:53], v[140:141], v[52:53]
	v_pk_fma_f32 v[96:97], v[64:65], v[64:65], v[96:97]
	v_pk_mul_f32 v[60:61], v[52:53], v[50:51]
	v_add_f32_e32 v52, v70, v71
	v_add_f32_e32 v52, v72, v52
	v_add_f32_e32 v52, v73, v52
	v_pk_mul_f32 v[50:51], v[60:61], v[60:61]
	v_add_f32_e32 v52, v52, v96
	v_pk_fma_f32 v[50:51], v[98:99], v[98:99], v[50:51]
	v_add_f32_e32 v52, v97, v52
	v_add_f32_e32 v50, v50, v52
	v_add_f32_e32 v50, v51, v50
	s_mov_b64 s[16:17], -1
	s_nop 1
	v_add_f32_dpp v50, v50, v50 quad_perm:[1,0,3,2] row_mask:0xf bank_mask:0xf
	s_nop 1
	v_add_f32_dpp v50, v50, v50 quad_perm:[2,3,0,1] row_mask:0xf bank_mask:0xf
	s_nop 1
	v_add_f32_dpp v50, v50, v50 row_half_mirror row_mask:0xf bank_mask:0xf
	s_nop 1
	v_add_f32_dpp v50, v50, v50 row_mirror row_mask:0xf bank_mask:0xf
	s_nop 0
	v_readlane_b32 s98, v50, 0
	v_readlane_b32 s99, v50, 16
	v_readlane_b32 s100, v50, 32
	v_readlane_b32 s101, v50, 48
	v_mov_b32_e32 v51, s98
	v_add_f32_e32 v51, s99, v51
	v_add_f32_e32 v51, s100, v51
	v_add_f32_e32 v50, s101, v51
	s_waitcnt lgkmcnt(0)
	v_fmamk_f32 v50, v50, 0x3a800000, v138
	v_mul_f32_e32 v51, 0x4b800000, v50
	v_cmp_gt_f32_e32 vcc, s23, v50
	s_nop 1
	v_cndmask_b32_e32 v50, v50, v51, vcc
	v_rsq_f32_e32 v52, v50
	v_lshlrev_b64 v[50:51], 12, v[66:67]
	v_lshl_add_u64 v[50:51], s[10:11], 0, v[50:51]
	v_lshl_add_u64 v[66:67], v[50:51], 0, v[74:75]
	v_mul_f32_e32 v50, 0x45800000, v52
	v_cndmask_b32_e32 v70, v52, v50, vcc
	v_pk_mul_f32 v[52:53], v[54:55], v[70:71] op_sel_hi:[1,0]
	v_pk_mul_f32 v[56:57], v[56:57], v[70:71] op_sel_hi:[1,0]
	v_pk_mul_f32 v[50:51], v[68:69], v[70:71] op_sel_hi:[1,0]
	v_pk_mul_f32 v[54:55], v[62:63], v[70:71] op_sel_hi:[1,0]
	v_bfe_u32 v62, v57, 16, 1
	v_bfe_u32 v63, v56, 16, 1
	v_bfe_u32 v68, v53, 16, 1
	v_bfe_u32 v69, v52, 16, 1
	v_add3_u32 v69, v52, v69, s24
	v_add3_u32 v68, v53, v68, s24
	v_add3_u32 v52, v56, v63, s24
	v_add3_u32 v53, v57, v62, s24
	v_bfe_u32 v56, v50, 16, 1
	v_bfe_u32 v57, v51, 16, 1
	v_bfe_u32 v62, v54, 16, 1
	v_bfe_u32 v63, v55, 16, 1
	v_add3_u32 v55, v55, v63, s24
	v_add3_u32 v54, v54, v62, s24
	v_add3_u32 v51, v51, v57, s24
	v_add3_u32 v50, v50, v56, s24
	v_lshrrev_b32_e32 v50, 16, v50
	v_lshrrev_b32_e32 v51, 16, v51
	v_lshrrev_b32_e32 v54, 16, v54
	v_lshrrev_b32_e32 v55, 16, v55
	v_and_or_b32 v53, v53, s22, v55
	v_and_or_b32 v52, v52, s22, v54
	v_and_or_b32 v51, v68, s22, v51
	v_and_or_b32 v50, v69, s22, v50
	global_store_dwordx4 v[66:67], v[50:53], off
	v_pk_mul_f32 v[56:57], v[60:61], v[70:71] op_sel_hi:[1,0]
	v_pk_mul_f32 v[54:55], v[98:99], v[70:71] op_sel_hi:[1,0]
	v_pk_mul_f32 v[52:53], v[58:59], v[70:71] op_sel_hi:[1,0]
	v_pk_mul_f32 v[50:51], v[64:65], v[70:71] op_sel_hi:[1,0]
	v_bfe_u32 v58, v57, 16, 1
	v_bfe_u32 v59, v56, 16, 1
	v_bfe_u32 v60, v53, 16, 1
	v_bfe_u32 v61, v52, 16, 1
	v_add3_u32 v61, v52, v61, s24
	v_add3_u32 v60, v53, v60, s24
	v_add3_u32 v52, v56, v59, s24
	v_add3_u32 v53, v57, v58, s24
	v_bfe_u32 v56, v50, 16, 1
	v_bfe_u32 v57, v51, 16, 1
	v_bfe_u32 v58, v54, 16, 1
	v_bfe_u32 v59, v55, 16, 1
	v_add3_u32 v55, v55, v59, s24
	v_add3_u32 v54, v54, v58, s24
	v_add3_u32 v51, v51, v57, s24
	v_add3_u32 v50, v50, v56, s24
	v_lshrrev_b32_e32 v50, 16, v50
	v_lshrrev_b32_e32 v51, 16, v51
	v_lshrrev_b32_e32 v54, 16, v54
	v_lshrrev_b32_e32 v55, 16, v55
	v_add_u32_e32 v58, s8, v126
	v_and_or_b32 v53, v53, s22, v55
	v_and_or_b32 v52, v52, s22, v54
	v_and_or_b32 v51, v60, s22, v51
	v_and_or_b32 v50, v61, s22, v50
	v_ashrrev_i32_e32 v59, 31, v58
	global_store_dwordx4 v[66:67], v[50:53], off offset:1024
	s_and_b64 vcc, exec, s[0:1]
	s_nop 0
	v_lshlrev_b64 v[50:51], 11, v[58:59]
	v_lshl_add_u64 v[60:61], s[6:7], 0, v[50:51]
	s_cbranch_vccnz .LBB0_799
	v_lshl_add_u64 v[50:51], v[60:61], 0, v[74:75]
	global_load_dwordx4 v[54:57], v[50:51], off nt
	s_cbranch_execz .LBB0_800

.LBB0_803:
	v_lshlrev_b32_e32 v60, 16, v46
	v_mul_f32_e32 v61, 0xbfb8aa3b, v60
	v_and_b32_e32 v46, 0xffff0000, v46
	v_exp_f32_e32 v62, v61
	v_lshlrev_b32_e32 v61, 16, v47
	v_mul_f32_e32 v63, 0xbfb8aa3b, v46
	v_exp_f32_e32 v63, v63
	v_mul_f32_e32 v64, 0xbfb8aa3b, v61
	v_exp_f32_e32 v65, v64
	v_and_b32_e32 v47, 0xffff0000, v47
	v_add_f32_e32 v63, 1.0, v63
	v_add_f32_e32 v62, 1.0, v62
	v_rcp_f32_e32 v64, v63
	v_add_f32_e32 v63, 1.0, v65
	v_mul_f32_e32 v65, 0xbfb8aa3b, v47
	v_rcp_f32_e32 v62, v62
	v_rcp_f32_e32 v63, v63
	v_exp_f32_e32 v65, v65
	s_waitcnt vmcnt(0) lgkmcnt(0)
	v_lshlrev_b32_e32 v67, 16, v55
	v_lshlrev_b32_e32 v66, 16, v54
	v_pk_mul_f32 v[60:61], v[62:63], v[60:61]
	v_add_f32_e32 v62, 1.0, v65
	v_rcp_f32_e32 v65, v62
	v_and_b32_e32 v55, 0xffff0000, v55
	v_and_b32_e32 v54, 0xffff0000, v54
	v_pk_mul_f32 v[60:61], v[60:61], v[66:67]
	v_pk_mul_f32 v[46:47], v[64:65], v[46:47]
	v_lshlrev_b32_e32 v69, 16, v57
	v_pk_mul_f32 v[46:47], v[46:47], v[54:55]
	v_lshlrev_b32_e32 v54, 16, v48
	v_mul_f32_e32 v55, 0xbfb8aa3b, v54
	v_and_b32_e32 v48, 0xffff0000, v48
	v_exp_f32_e32 v64, v55
	v_lshlrev_b32_e32 v55, 16, v49
	v_mul_f32_e32 v65, 0xbfb8aa3b, v48
	v_exp_f32_e32 v65, v65
	v_mul_f32_e32 v66, 0xbfb8aa3b, v55
	v_exp_f32_e32 v67, v66
	v_and_b32_e32 v49, 0xffff0000, v49
	v_add_f32_e32 v65, 1.0, v65
	v_add_f32_e32 v64, 1.0, v64
	v_rcp_f32_e32 v66, v65
	v_add_f32_e32 v65, 1.0, v67
	v_mul_f32_e32 v67, 0xbfb8aa3b, v49
	v_rcp_f32_e32 v64, v64
	v_rcp_f32_e32 v65, v65
	v_exp_f32_e32 v67, v67
	v_lshlrev_b32_e32 v68, 16, v56
	v_and_b32_e32 v57, 0xffff0000, v57
	v_pk_mul_f32 v[54:55], v[64:65], v[54:55]
	v_add_f32_e32 v64, 1.0, v67
	v_rcp_f32_e32 v67, v64
	v_and_b32_e32 v56, 0xffff0000, v56
	v_pk_mul_f32 v[54:55], v[54:55], v[68:69]
	v_lshlrev_b32_e32 v71, 16, v51
	v_pk_mul_f32 v[48:49], v[66:67], v[48:49]
	v_lshlrev_b32_e32 v70, 16, v50
	v_pk_mul_f32 v[48:49], v[48:49], v[56:57]
	v_lshlrev_b32_e32 v56, 16, v42
	v_mul_f32_e32 v57, 0xbfb8aa3b, v56
	v_and_b32_e32 v42, 0xffff0000, v42
	v_exp_f32_e32 v66, v57
	v_lshlrev_b32_e32 v57, 16, v43
	v_mul_f32_e32 v67, 0xbfb8aa3b, v42
	v_exp_f32_e32 v67, v67
	v_mul_f32_e32 v68, 0xbfb8aa3b, v57
	v_exp_f32_e32 v69, v68
	v_and_b32_e32 v43, 0xffff0000, v43
	v_add_f32_e32 v67, 1.0, v67
	v_add_f32_e32 v66, 1.0, v66
	v_rcp_f32_e32 v68, v67
	v_add_f32_e32 v67, 1.0, v69
	v_mul_f32_e32 v69, 0xbfb8aa3b, v43
	v_rcp_f32_e32 v66, v66
	v_rcp_f32_e32 v67, v67
	v_exp_f32_e32 v69, v69
	v_and_b32_e32 v51, 0xffff0000, v51
	v_and_b32_e32 v50, 0xffff0000, v50
	v_pk_mul_f32 v[56:57], v[66:67], v[56:57]
	v_add_f32_e32 v66, 1.0, v69
	v_rcp_f32_e32 v69, v66
	v_pk_mul_f32 v[56:57], v[56:57], v[70:71]
	v_pk_mul_f32 v[62:63], v[46:47], v[46:47]
	v_lshlrev_b32_e32 v73, 16, v53
	v_pk_mul_f32 v[42:43], v[68:69], v[42:43]
	v_lshlrev_b32_e32 v72, 16, v52
	v_pk_mul_f32 v[50:51], v[42:43], v[50:51]
	v_lshlrev_b32_e32 v42, 16, v44
	v_mul_f32_e32 v43, 0xbfb8aa3b, v42
	v_and_b32_e32 v44, 0xffff0000, v44
	v_exp_f32_e32 v68, v43
	v_lshlrev_b32_e32 v43, 16, v45
	v_mul_f32_e32 v69, 0xbfb8aa3b, v44
	v_exp_f32_e32 v69, v69
	v_mul_f32_e32 v70, 0xbfb8aa3b, v43
	v_exp_f32_e32 v71, v70
	v_and_b32_e32 v45, 0xffff0000, v45
	v_add_f32_e32 v69, 1.0, v69
	v_add_f32_e32 v68, 1.0, v68
	v_rcp_f32_e32 v70, v69
	v_add_f32_e32 v69, 1.0, v71
	v_mul_f32_e32 v71, 0xbfb8aa3b, v45
	v_rcp_f32_e32 v68, v68
	v_rcp_f32_e32 v69, v69
	v_exp_f32_e32 v71, v71
	v_pk_fma_f32 v[62:63], v[60:61], v[60:61], v[62:63]
	v_pk_mul_f32 v[64:65], v[48:49], v[48:49]
	v_pk_mul_f32 v[42:43], v[68:69], v[42:43]
	v_add_f32_e32 v68, 1.0, v71
	v_rcp_f32_e32 v71, v68
	v_pk_mul_f32 v[68:69], v[42:43], v[72:73]
	v_and_b32_e32 v43, 0xffff0000, v53
	v_and_b32_e32 v42, 0xffff0000, v52
	v_pk_mul_f32 v[44:45], v[70:71], v[44:45]
	v_pk_fma_f32 v[64:65], v[54:55], v[54:55], v[64:65]
	v_pk_mul_f32 v[52:53], v[44:45], v[42:43]
	v_add_f32_e32 v44, v62, v63
	v_pk_mul_f32 v[66:67], v[50:51], v[50:51]
	v_add_f32_e32 v44, v64, v44
	v_pk_fma_f32 v[66:67], v[56:57], v[56:57], v[66:67]
	v_add_f32_e32 v44, v65, v44
	v_pk_mul_f32 v[42:43], v[52:53], v[52:53]
	v_add_f32_e32 v44, v44, v66
	v_pk_fma_f32 v[42:43], v[68:69], v[68:69], v[42:43]
	v_add_f32_e32 v44, v67, v44
	v_add_f32_e32 v42, v42, v44
	v_add_f32_e32 v42, v43, v42
	s_mov_b64 s[16:17], -1
	s_nop 1
	v_add_f32_dpp v42, v42, v42 quad_perm:[1,0,3,2] row_mask:0xf bank_mask:0xf
	s_nop 1
	v_add_f32_dpp v42, v42, v42 quad_perm:[2,3,0,1] row_mask:0xf bank_mask:0xf
	s_nop 1
	v_add_f32_dpp v42, v42, v42 row_half_mirror row_mask:0xf bank_mask:0xf
	s_nop 1
	v_add_f32_dpp v42, v42, v42 row_mirror row_mask:0xf bank_mask:0xf
	s_nop 0
	v_readlane_b32 s98, v42, 0
	v_readlane_b32 s99, v42, 16
	v_readlane_b32 s100, v42, 32
	v_readlane_b32 s101, v42, 48
	v_mov_b32_e32 v43, s98
	v_add_f32_e32 v43, s99, v43
	v_add_f32_e32 v43, s100, v43
	v_add_f32_e32 v42, s101, v43
	s_waitcnt lgkmcnt(0)
	v_fmamk_f32 v42, v42, 0x3a800000, v138
	v_mul_f32_e32 v43, 0x4b800000, v42
	v_cmp_gt_f32_e32 vcc, s23, v42
	s_nop 1
	v_cndmask_b32_e32 v42, v42, v43, vcc
	v_rsq_f32_e32 v44, v42
	v_lshlrev_b64 v[42:43], 12, v[58:59]
	v_lshl_add_u64 v[42:43], s[10:11], 0, v[42:43]
	v_lshl_add_u64 v[58:59], v[42:43], 0, v[74:75]
	v_mul_f32_e32 v42, 0x45800000, v44
	v_cndmask_b32_e32 v62, v44, v42, vcc
	v_pk_mul_f32 v[44:45], v[46:47], v[62:63] op_sel_hi:[1,0]
	v_pk_mul_f32 v[48:49], v[48:49], v[62:63] op_sel_hi:[1,0]
	v_pk_mul_f32 v[42:43], v[60:61], v[62:63] op_sel_hi:[1,0]
	v_pk_mul_f32 v[46:47], v[54:55], v[62:63] op_sel_hi:[1,0]
	v_bfe_u32 v54, v49, 16, 1
	v_bfe_u32 v55, v48, 16, 1
	v_bfe_u32 v60, v45, 16, 1
	v_bfe_u32 v61, v44, 16, 1
	v_add3_u32 v61, v44, v61, s24
	v_add3_u32 v60, v45, v60, s24
	v_add3_u32 v44, v48, v55, s24
	v_add3_u32 v45, v49, v54, s24
	v_bfe_u32 v48, v42, 16, 1
	v_bfe_u32 v49, v43, 16, 1
	v_bfe_u32 v54, v46, 16, 1
	v_bfe_u32 v55, v47, 16, 1
	v_add3_u32 v47, v47, v55, s24
	v_add3_u32 v46, v46, v54, s24
	v_add3_u32 v43, v43, v49, s24
	v_add3_u32 v42, v42, v48, s24
	v_lshrrev_b32_e32 v42, 16, v42
	v_lshrrev_b32_e32 v43, 16, v43
	v_lshrrev_b32_e32 v46, 16, v46
	v_lshrrev_b32_e32 v47, 16, v47
	v_and_or_b32 v45, v45, s22, v47
	v_and_or_b32 v44, v44, s22, v46
	v_and_or_b32 v43, v60, s22, v43
	v_and_or_b32 v42, v61, s22, v42
	global_store_dwordx4 v[58:59], v[42:45], off
	v_pk_mul_f32 v[48:49], v[52:53], v[62:63] op_sel_hi:[1,0]
	v_pk_mul_f32 v[46:47], v[68:69], v[62:63] op_sel_hi:[1,0]
	v_pk_mul_f32 v[44:45], v[50:51], v[62:63] op_sel_hi:[1,0]
	v_pk_mul_f32 v[42:43], v[56:57], v[62:63] op_sel_hi:[1,0]
	v_bfe_u32 v50, v49, 16, 1
	v_bfe_u32 v51, v48, 16, 1
	v_bfe_u32 v52, v45, 16, 1
	v_bfe_u32 v53, v44, 16, 1
	v_add3_u32 v53, v44, v53, s24
	v_add3_u32 v52, v45, v52, s24
	v_add3_u32 v44, v48, v51, s24
	v_add3_u32 v45, v49, v50, s24
	v_bfe_u32 v48, v42, 16, 1
	v_bfe_u32 v49, v43, 16, 1
	v_bfe_u32 v50, v46, 16, 1
	v_bfe_u32 v51, v47, 16, 1
	v_add3_u32 v47, v47, v51, s24
	v_add3_u32 v46, v46, v50, s24
	v_add3_u32 v43, v43, v49, s24
	v_add3_u32 v42, v42, v48, s24
	v_lshrrev_b32_e32 v42, 16, v42
	v_lshrrev_b32_e32 v43, 16, v43
	v_lshrrev_b32_e32 v46, 16, v46
	v_lshrrev_b32_e32 v47, 16, v47
	v_add_u32_e32 v50, s8, v128
	v_and_or_b32 v45, v45, s22, v47
	v_and_or_b32 v44, v44, s22, v46
	v_and_or_b32 v43, v52, s22, v43
	v_and_or_b32 v42, v53, s22, v42
	v_ashrrev_i32_e32 v51, 31, v50
	global_store_dwordx4 v[58:59], v[42:45], off offset:1024
	s_and_b64 vcc, exec, s[0:1]
	s_nop 0
	v_lshlrev_b64 v[42:43], 11, v[50:51]
	v_lshl_add_u64 v[52:53], s[6:7], 0, v[42:43]
	s_cbranch_vccnz .LBB0_807
	v_lshl_add_u64 v[42:43], v[52:53], 0, v[74:75]
	global_load_dwordx4 v[46:49], v[42:43], off nt
	s_cbranch_execz .LBB0_808

.LBB0_811:
	v_lshlrev_b32_e32 v52, 16, v38
	v_mul_f32_e32 v53, 0xbfb8aa3b, v52
	v_and_b32_e32 v38, 0xffff0000, v38
	v_exp_f32_e32 v54, v53
	v_lshlrev_b32_e32 v53, 16, v39
	v_mul_f32_e32 v55, 0xbfb8aa3b, v38
	v_exp_f32_e32 v55, v55
	v_mul_f32_e32 v56, 0xbfb8aa3b, v53
	v_exp_f32_e32 v57, v56
	v_and_b32_e32 v39, 0xffff0000, v39
	v_add_f32_e32 v55, 1.0, v55
	v_add_f32_e32 v54, 1.0, v54
	v_rcp_f32_e32 v56, v55
	v_add_f32_e32 v55, 1.0, v57
	v_mul_f32_e32 v57, 0xbfb8aa3b, v39
	v_rcp_f32_e32 v54, v54
	v_rcp_f32_e32 v55, v55
	v_exp_f32_e32 v57, v57
	s_waitcnt vmcnt(0) lgkmcnt(0)
	v_lshlrev_b32_e32 v59, 16, v47
	v_lshlrev_b32_e32 v58, 16, v46
	v_pk_mul_f32 v[52:53], v[54:55], v[52:53]
	v_add_f32_e32 v54, 1.0, v57
	v_rcp_f32_e32 v57, v54
	v_and_b32_e32 v47, 0xffff0000, v47
	v_and_b32_e32 v46, 0xffff0000, v46
	v_pk_mul_f32 v[52:53], v[52:53], v[58:59]
	v_pk_mul_f32 v[38:39], v[56:57], v[38:39]
	v_lshlrev_b32_e32 v61, 16, v49
	v_pk_mul_f32 v[38:39], v[38:39], v[46:47]
	v_lshlrev_b32_e32 v46, 16, v40
	v_mul_f32_e32 v47, 0xbfb8aa3b, v46
	v_and_b32_e32 v40, 0xffff0000, v40
	v_exp_f32_e32 v56, v47
	v_lshlrev_b32_e32 v47, 16, v41
	v_mul_f32_e32 v57, 0xbfb8aa3b, v40
	v_exp_f32_e32 v57, v57
	v_mul_f32_e32 v58, 0xbfb8aa3b, v47
	v_exp_f32_e32 v59, v58
	v_and_b32_e32 v41, 0xffff0000, v41
	v_add_f32_e32 v57, 1.0, v57
	v_add_f32_e32 v56, 1.0, v56
	v_rcp_f32_e32 v58, v57
	v_add_f32_e32 v57, 1.0, v59
	v_mul_f32_e32 v59, 0xbfb8aa3b, v41
	v_rcp_f32_e32 v56, v56
	v_rcp_f32_e32 v57, v57
	v_exp_f32_e32 v59, v59
	v_lshlrev_b32_e32 v60, 16, v48
	v_and_b32_e32 v49, 0xffff0000, v49
	v_pk_mul_f32 v[46:47], v[56:57], v[46:47]
	v_add_f32_e32 v56, 1.0, v59
	v_rcp_f32_e32 v59, v56
	v_and_b32_e32 v48, 0xffff0000, v48
	v_pk_mul_f32 v[46:47], v[46:47], v[60:61]
	v_lshlrev_b32_e32 v63, 16, v43
	v_pk_mul_f32 v[40:41], v[58:59], v[40:41]
	v_lshlrev_b32_e32 v62, 16, v42
	v_pk_mul_f32 v[40:41], v[40:41], v[48:49]
	v_lshlrev_b32_e32 v48, 16, v34
	v_mul_f32_e32 v49, 0xbfb8aa3b, v48
	v_and_b32_e32 v34, 0xffff0000, v34
	v_exp_f32_e32 v58, v49
	v_lshlrev_b32_e32 v49, 16, v35
	v_mul_f32_e32 v59, 0xbfb8aa3b, v34
	v_exp_f32_e32 v59, v59
	v_mul_f32_e32 v60, 0xbfb8aa3b, v49
	v_exp_f32_e32 v61, v60
	v_and_b32_e32 v35, 0xffff0000, v35
	v_add_f32_e32 v59, 1.0, v59
	v_add_f32_e32 v58, 1.0, v58
	v_rcp_f32_e32 v60, v59
	v_add_f32_e32 v59, 1.0, v61
	v_mul_f32_e32 v61, 0xbfb8aa3b, v35
	v_rcp_f32_e32 v58, v58
	v_rcp_f32_e32 v59, v59
	v_exp_f32_e32 v61, v61
	v_and_b32_e32 v43, 0xffff0000, v43
	v_and_b32_e32 v42, 0xffff0000, v42
	v_pk_mul_f32 v[48:49], v[58:59], v[48:49]
	v_add_f32_e32 v58, 1.0, v61
	v_rcp_f32_e32 v61, v58
	v_pk_mul_f32 v[48:49], v[48:49], v[62:63]
	v_pk_mul_f32 v[54:55], v[38:39], v[38:39]
	v_lshlrev_b32_e32 v65, 16, v45
	v_pk_mul_f32 v[34:35], v[60:61], v[34:35]
	v_lshlrev_b32_e32 v64, 16, v44
	v_pk_mul_f32 v[42:43], v[34:35], v[42:43]
	v_lshlrev_b32_e32 v34, 16, v36
	v_mul_f32_e32 v35, 0xbfb8aa3b, v34
	v_and_b32_e32 v36, 0xffff0000, v36
	v_exp_f32_e32 v60, v35
	v_lshlrev_b32_e32 v35, 16, v37
	v_mul_f32_e32 v61, 0xbfb8aa3b, v36
	v_exp_f32_e32 v61, v61
	v_mul_f32_e32 v62, 0xbfb8aa3b, v35
	v_exp_f32_e32 v63, v62
	v_and_b32_e32 v37, 0xffff0000, v37
	v_add_f32_e32 v61, 1.0, v61
	v_add_f32_e32 v60, 1.0, v60
	v_rcp_f32_e32 v62, v61
	v_add_f32_e32 v61, 1.0, v63
	v_mul_f32_e32 v63, 0xbfb8aa3b, v37
	v_rcp_f32_e32 v60, v60
	v_rcp_f32_e32 v61, v61
	v_exp_f32_e32 v63, v63
	v_pk_fma_f32 v[54:55], v[52:53], v[52:53], v[54:55]
	v_pk_mul_f32 v[56:57], v[40:41], v[40:41]
	v_pk_mul_f32 v[34:35], v[60:61], v[34:35]
	v_add_f32_e32 v60, 1.0, v63
	v_rcp_f32_e32 v63, v60
	v_pk_mul_f32 v[60:61], v[34:35], v[64:65]
	v_and_b32_e32 v35, 0xffff0000, v45
	v_and_b32_e32 v34, 0xffff0000, v44
	v_pk_mul_f32 v[36:37], v[62:63], v[36:37]
	v_pk_fma_f32 v[56:57], v[46:47], v[46:47], v[56:57]
	v_pk_mul_f32 v[44:45], v[36:37], v[34:35]
	v_add_f32_e32 v36, v54, v55
	v_pk_mul_f32 v[58:59], v[42:43], v[42:43]
	v_add_f32_e32 v36, v56, v36
	v_pk_fma_f32 v[58:59], v[48:49], v[48:49], v[58:59]
	v_add_f32_e32 v36, v57, v36
	v_pk_mul_f32 v[34:35], v[44:45], v[44:45]
	v_add_f32_e32 v36, v36, v58
	v_pk_fma_f32 v[34:35], v[60:61], v[60:61], v[34:35]
	v_add_f32_e32 v36, v59, v36
	v_add_f32_e32 v34, v34, v36
	v_add_f32_e32 v34, v35, v34
	s_mov_b64 s[16:17], -1
	s_nop 1
	v_add_f32_dpp v34, v34, v34 quad_perm:[1,0,3,2] row_mask:0xf bank_mask:0xf
	s_nop 1
	v_add_f32_dpp v34, v34, v34 quad_perm:[2,3,0,1] row_mask:0xf bank_mask:0xf
	s_nop 1
	v_add_f32_dpp v34, v34, v34 row_half_mirror row_mask:0xf bank_mask:0xf
	s_nop 1
	v_add_f32_dpp v34, v34, v34 row_mirror row_mask:0xf bank_mask:0xf
	s_nop 0
	v_readlane_b32 s98, v34, 0
	v_readlane_b32 s99, v34, 16
	v_readlane_b32 s100, v34, 32
	v_readlane_b32 s101, v34, 48
	v_mov_b32_e32 v35, s98
	v_add_f32_e32 v35, s99, v35
	v_add_f32_e32 v35, s100, v35
	v_add_f32_e32 v34, s101, v35
	s_waitcnt lgkmcnt(0)
	v_fmamk_f32 v34, v34, 0x3a800000, v138
	v_mul_f32_e32 v35, 0x4b800000, v34
	v_cmp_gt_f32_e32 vcc, s23, v34
	s_nop 1
	v_cndmask_b32_e32 v34, v34, v35, vcc
	v_rsq_f32_e32 v36, v34
	v_lshlrev_b64 v[34:35], 12, v[50:51]
	v_lshl_add_u64 v[34:35], s[10:11], 0, v[34:35]
	v_lshl_add_u64 v[50:51], v[34:35], 0, v[74:75]
	v_mul_f32_e32 v34, 0x45800000, v36
	v_cndmask_b32_e32 v54, v36, v34, vcc
	v_pk_mul_f32 v[36:37], v[38:39], v[54:55] op_sel_hi:[1,0]
	v_pk_mul_f32 v[40:41], v[40:41], v[54:55] op_sel_hi:[1,0]
	v_pk_mul_f32 v[34:35], v[52:53], v[54:55] op_sel_hi:[1,0]
	v_pk_mul_f32 v[38:39], v[46:47], v[54:55] op_sel_hi:[1,0]
	v_bfe_u32 v46, v41, 16, 1
	v_bfe_u32 v47, v40, 16, 1
	v_bfe_u32 v52, v37, 16, 1
	v_bfe_u32 v53, v36, 16, 1
	v_add3_u32 v53, v36, v53, s24
	v_add3_u32 v52, v37, v52, s24
	v_add3_u32 v36, v40, v47, s24
	v_add3_u32 v37, v41, v46, s24
	v_bfe_u32 v40, v34, 16, 1
	v_bfe_u32 v41, v35, 16, 1
	v_bfe_u32 v46, v38, 16, 1
	v_bfe_u32 v47, v39, 16, 1
	v_add3_u32 v39, v39, v47, s24
	v_add3_u32 v38, v38, v46, s24
	v_add3_u32 v35, v35, v41, s24
	v_add3_u32 v34, v34, v40, s24
	v_lshrrev_b32_e32 v34, 16, v34
	v_lshrrev_b32_e32 v35, 16, v35
	v_lshrrev_b32_e32 v38, 16, v38
	v_lshrrev_b32_e32 v39, 16, v39
	v_and_or_b32 v37, v37, s22, v39
	v_and_or_b32 v36, v36, s22, v38
	v_and_or_b32 v35, v52, s22, v35
	v_and_or_b32 v34, v53, s22, v34
	global_store_dwordx4 v[50:51], v[34:37], off
	v_pk_mul_f32 v[40:41], v[44:45], v[54:55] op_sel_hi:[1,0]
	v_pk_mul_f32 v[38:39], v[60:61], v[54:55] op_sel_hi:[1,0]
	v_pk_mul_f32 v[36:37], v[42:43], v[54:55] op_sel_hi:[1,0]
	v_pk_mul_f32 v[34:35], v[48:49], v[54:55] op_sel_hi:[1,0]
	v_bfe_u32 v42, v41, 16, 1
	v_bfe_u32 v43, v40, 16, 1
	v_bfe_u32 v44, v37, 16, 1
	v_bfe_u32 v45, v36, 16, 1
	v_add3_u32 v45, v36, v45, s24
	v_add3_u32 v44, v37, v44, s24
	v_add3_u32 v36, v40, v43, s24
	v_add3_u32 v37, v41, v42, s24
	v_bfe_u32 v40, v34, 16, 1
	v_bfe_u32 v41, v35, 16, 1
	v_bfe_u32 v42, v38, 16, 1
	v_bfe_u32 v43, v39, 16, 1
	v_add3_u32 v39, v39, v43, s24
	v_add3_u32 v38, v38, v42, s24
	v_add3_u32 v35, v35, v41, s24
	v_add3_u32 v34, v34, v40, s24
	v_lshrrev_b32_e32 v34, 16, v34
	v_lshrrev_b32_e32 v35, 16, v35
	v_lshrrev_b32_e32 v38, 16, v38
	v_lshrrev_b32_e32 v39, 16, v39
	v_add_u32_e32 v42, s8, v130
	v_and_or_b32 v37, v37, s22, v39
	v_and_or_b32 v36, v36, s22, v38
	v_and_or_b32 v35, v44, s22, v35
	v_and_or_b32 v34, v45, s22, v34
	v_ashrrev_i32_e32 v43, 31, v42
	global_store_dwordx4 v[50:51], v[34:37], off offset:1024
	s_and_b64 vcc, exec, s[0:1]
	s_nop 0
	v_lshlrev_b64 v[34:35], 11, v[42:43]
	v_lshl_add_u64 v[44:45], s[6:7], 0, v[34:35]
	s_cbranch_vccnz .LBB0_815
	v_lshl_add_u64 v[34:35], v[44:45], 0, v[74:75]
	global_load_dwordx4 v[38:41], v[34:35], off nt
	s_cbranch_execz .LBB0_816

.LBB0_819:
	v_lshlrev_b32_e32 v44, 16, v30
	v_mul_f32_e32 v45, 0xbfb8aa3b, v44
	v_and_b32_e32 v30, 0xffff0000, v30
	v_exp_f32_e32 v46, v45
	v_lshlrev_b32_e32 v45, 16, v31
	v_mul_f32_e32 v47, 0xbfb8aa3b, v30
	v_exp_f32_e32 v47, v47
	v_mul_f32_e32 v48, 0xbfb8aa3b, v45
	v_exp_f32_e32 v49, v48
	v_and_b32_e32 v31, 0xffff0000, v31
	v_add_f32_e32 v47, 1.0, v47
	v_add_f32_e32 v46, 1.0, v46
	v_rcp_f32_e32 v48, v47
	v_add_f32_e32 v47, 1.0, v49
	v_mul_f32_e32 v49, 0xbfb8aa3b, v31
	v_rcp_f32_e32 v46, v46
	v_rcp_f32_e32 v47, v47
	v_exp_f32_e32 v49, v49
	s_waitcnt vmcnt(0) lgkmcnt(0)
	v_lshlrev_b32_e32 v51, 16, v39
	v_lshlrev_b32_e32 v50, 16, v38
	v_pk_mul_f32 v[44:45], v[46:47], v[44:45]
	v_add_f32_e32 v46, 1.0, v49
	v_rcp_f32_e32 v49, v46
	v_and_b32_e32 v39, 0xffff0000, v39
	v_and_b32_e32 v38, 0xffff0000, v38
	v_pk_mul_f32 v[44:45], v[44:45], v[50:51]
	v_pk_mul_f32 v[30:31], v[48:49], v[30:31]
	v_lshlrev_b32_e32 v53, 16, v41
	v_pk_mul_f32 v[30:31], v[30:31], v[38:39]
	v_lshlrev_b32_e32 v38, 16, v32
	v_mul_f32_e32 v39, 0xbfb8aa3b, v38
	v_and_b32_e32 v32, 0xffff0000, v32
	v_exp_f32_e32 v48, v39
	v_lshlrev_b32_e32 v39, 16, v33
	v_mul_f32_e32 v49, 0xbfb8aa3b, v32
	v_exp_f32_e32 v49, v49
	v_mul_f32_e32 v50, 0xbfb8aa3b, v39
	v_exp_f32_e32 v51, v50
	v_and_b32_e32 v33, 0xffff0000, v33
	v_add_f32_e32 v49, 1.0, v49
	v_add_f32_e32 v48, 1.0, v48
	v_rcp_f32_e32 v50, v49
	v_add_f32_e32 v49, 1.0, v51
	v_mul_f32_e32 v51, 0xbfb8aa3b, v33
	v_rcp_f32_e32 v48, v48
	v_rcp_f32_e32 v49, v49
	v_exp_f32_e32 v51, v51
	v_lshlrev_b32_e32 v52, 16, v40
	v_and_b32_e32 v41, 0xffff0000, v41
	v_pk_mul_f32 v[38:39], v[48:49], v[38:39]
	v_add_f32_e32 v48, 1.0, v51
	v_rcp_f32_e32 v51, v48
	v_and_b32_e32 v40, 0xffff0000, v40
	v_pk_mul_f32 v[38:39], v[38:39], v[52:53]
	v_lshlrev_b32_e32 v55, 16, v35
	v_pk_mul_f32 v[32:33], v[50:51], v[32:33]
	v_lshlrev_b32_e32 v54, 16, v34
	v_pk_mul_f32 v[32:33], v[32:33], v[40:41]
	v_lshlrev_b32_e32 v40, 16, v26
	v_mul_f32_e32 v41, 0xbfb8aa3b, v40
	v_and_b32_e32 v26, 0xffff0000, v26
	v_exp_f32_e32 v50, v41
	v_lshlrev_b32_e32 v41, 16, v27
	v_mul_f32_e32 v51, 0xbfb8aa3b, v26
	v_exp_f32_e32 v51, v51
	v_mul_f32_e32 v52, 0xbfb8aa3b, v41
	v_exp_f32_e32 v53, v52
	v_and_b32_e32 v27, 0xffff0000, v27
	v_add_f32_e32 v51, 1.0, v51
	v_add_f32_e32 v50, 1.0, v50
	v_rcp_f32_e32 v52, v51
	v_add_f32_e32 v51, 1.0, v53
	v_mul_f32_e32 v53, 0xbfb8aa3b, v27
	v_rcp_f32_e32 v50, v50
	v_rcp_f32_e32 v51, v51
	v_exp_f32_e32 v53, v53
	v_and_b32_e32 v35, 0xffff0000, v35
	v_and_b32_e32 v34, 0xffff0000, v34
	v_pk_mul_f32 v[40:41], v[50:51], v[40:41]
	v_add_f32_e32 v50, 1.0, v53
	v_rcp_f32_e32 v53, v50
	v_pk_mul_f32 v[40:41], v[40:41], v[54:55]
	v_pk_mul_f32 v[46:47], v[30:31], v[30:31]
	v_lshlrev_b32_e32 v57, 16, v37
	v_pk_mul_f32 v[26:27], v[52:53], v[26:27]
	v_lshlrev_b32_e32 v56, 16, v36
	v_pk_mul_f32 v[34:35], v[26:27], v[34:35]
	v_lshlrev_b32_e32 v26, 16, v28
	v_mul_f32_e32 v27, 0xbfb8aa3b, v26
	v_and_b32_e32 v28, 0xffff0000, v28
	v_exp_f32_e32 v52, v27
	v_lshlrev_b32_e32 v27, 16, v29
	v_mul_f32_e32 v53, 0xbfb8aa3b, v28
	v_exp_f32_e32 v53, v53
	v_mul_f32_e32 v54, 0xbfb8aa3b, v27
	v_exp_f32_e32 v55, v54
	v_and_b32_e32 v29, 0xffff0000, v29
	v_add_f32_e32 v53, 1.0, v53
	v_add_f32_e32 v52, 1.0, v52
	v_rcp_f32_e32 v54, v53
	v_add_f32_e32 v53, 1.0, v55
	v_mul_f32_e32 v55, 0xbfb8aa3b, v29
	v_rcp_f32_e32 v52, v52
	v_rcp_f32_e32 v53, v53
	v_exp_f32_e32 v55, v55
	v_pk_fma_f32 v[46:47], v[44:45], v[44:45], v[46:47]
	v_pk_mul_f32 v[48:49], v[32:33], v[32:33]
	v_pk_mul_f32 v[26:27], v[52:53], v[26:27]
	v_add_f32_e32 v52, 1.0, v55
	v_rcp_f32_e32 v55, v52
	v_pk_mul_f32 v[52:53], v[26:27], v[56:57]
	v_and_b32_e32 v27, 0xffff0000, v37
	v_and_b32_e32 v26, 0xffff0000, v36
	v_pk_mul_f32 v[28:29], v[54:55], v[28:29]
	v_pk_fma_f32 v[48:49], v[38:39], v[38:39], v[48:49]
	v_pk_mul_f32 v[36:37], v[28:29], v[26:27]
	v_add_f32_e32 v28, v46, v47
	v_pk_mul_f32 v[50:51], v[34:35], v[34:35]
	v_add_f32_e32 v28, v48, v28
	v_pk_fma_f32 v[50:51], v[40:41], v[40:41], v[50:51]
	v_add_f32_e32 v28, v49, v28
	v_pk_mul_f32 v[26:27], v[36:37], v[36:37]
	v_add_f32_e32 v28, v28, v50
	v_pk_fma_f32 v[26:27], v[52:53], v[52:53], v[26:27]
	v_add_f32_e32 v28, v51, v28
	v_add_f32_e32 v26, v26, v28
	v_add_f32_e32 v26, v27, v26
	s_mov_b64 s[16:17], -1
	s_nop 1
	v_add_f32_dpp v26, v26, v26 quad_perm:[1,0,3,2] row_mask:0xf bank_mask:0xf
	s_nop 1
	v_add_f32_dpp v26, v26, v26 quad_perm:[2,3,0,1] row_mask:0xf bank_mask:0xf
	s_nop 1
	v_add_f32_dpp v26, v26, v26 row_half_mirror row_mask:0xf bank_mask:0xf
	s_nop 1
	v_add_f32_dpp v26, v26, v26 row_mirror row_mask:0xf bank_mask:0xf
	s_nop 0
	v_readlane_b32 s98, v26, 0
	v_readlane_b32 s99, v26, 16
	v_readlane_b32 s100, v26, 32
	v_readlane_b32 s101, v26, 48
	v_mov_b32_e32 v27, s98
	v_add_f32_e32 v27, s99, v27
	v_add_f32_e32 v27, s100, v27
	v_add_f32_e32 v26, s101, v27
	s_waitcnt lgkmcnt(0)
	v_fmamk_f32 v26, v26, 0x3a800000, v138
	v_mul_f32_e32 v27, 0x4b800000, v26
	v_cmp_gt_f32_e32 vcc, s23, v26
	s_nop 1
	v_cndmask_b32_e32 v26, v26, v27, vcc
	v_rsq_f32_e32 v28, v26
	v_lshlrev_b64 v[26:27], 12, v[42:43]
	v_lshl_add_u64 v[26:27], s[10:11], 0, v[26:27]
	v_lshl_add_u64 v[42:43], v[26:27], 0, v[74:75]
	v_mul_f32_e32 v26, 0x45800000, v28
	v_cndmask_b32_e32 v46, v28, v26, vcc
	v_pk_mul_f32 v[28:29], v[30:31], v[46:47] op_sel_hi:[1,0]
	v_pk_mul_f32 v[32:33], v[32:33], v[46:47] op_sel_hi:[1,0]
	v_pk_mul_f32 v[26:27], v[44:45], v[46:47] op_sel_hi:[1,0]
	v_pk_mul_f32 v[30:31], v[38:39], v[46:47] op_sel_hi:[1,0]
	v_bfe_u32 v38, v33, 16, 1
	v_bfe_u32 v39, v32, 16, 1
	v_bfe_u32 v44, v29, 16, 1
	v_bfe_u32 v45, v28, 16, 1
	v_add3_u32 v45, v28, v45, s24
	v_add3_u32 v44, v29, v44, s24
	v_add3_u32 v28, v32, v39, s24
	v_add3_u32 v29, v33, v38, s24
	v_bfe_u32 v32, v26, 16, 1
	v_bfe_u32 v33, v27, 16, 1
	v_bfe_u32 v38, v30, 16, 1
	v_bfe_u32 v39, v31, 16, 1
	v_add3_u32 v31, v31, v39, s24
	v_add3_u32 v30, v30, v38, s24
	v_add3_u32 v27, v27, v33, s24
	v_add3_u32 v26, v26, v32, s24
	v_lshrrev_b32_e32 v26, 16, v26
	v_lshrrev_b32_e32 v27, 16, v27
	v_lshrrev_b32_e32 v30, 16, v30
	v_lshrrev_b32_e32 v31, 16, v31
	v_and_or_b32 v29, v29, s22, v31
	v_and_or_b32 v28, v28, s22, v30
	v_and_or_b32 v27, v44, s22, v27
	v_and_or_b32 v26, v45, s22, v26
	global_store_dwordx4 v[42:43], v[26:29], off
	v_pk_mul_f32 v[32:33], v[36:37], v[46:47] op_sel_hi:[1,0]
	v_pk_mul_f32 v[30:31], v[52:53], v[46:47] op_sel_hi:[1,0]
	v_pk_mul_f32 v[28:29], v[34:35], v[46:47] op_sel_hi:[1,0]
	v_pk_mul_f32 v[26:27], v[40:41], v[46:47] op_sel_hi:[1,0]
	v_bfe_u32 v34, v33, 16, 1
	v_bfe_u32 v35, v32, 16, 1
	v_bfe_u32 v36, v29, 16, 1
	v_bfe_u32 v37, v28, 16, 1
	v_add3_u32 v37, v28, v37, s24
	v_add3_u32 v36, v29, v36, s24
	v_add3_u32 v28, v32, v35, s24
	v_add3_u32 v29, v33, v34, s24
	v_bfe_u32 v32, v26, 16, 1
	v_bfe_u32 v33, v27, 16, 1
	v_bfe_u32 v34, v30, 16, 1
	v_bfe_u32 v35, v31, 16, 1
	v_add3_u32 v31, v31, v35, s24
	v_add3_u32 v30, v30, v34, s24
	v_add3_u32 v27, v27, v33, s24
	v_add3_u32 v26, v26, v32, s24
	v_lshrrev_b32_e32 v26, 16, v26
	v_lshrrev_b32_e32 v27, 16, v27
	v_lshrrev_b32_e32 v30, 16, v30
	v_lshrrev_b32_e32 v31, 16, v31
	v_add_u32_e32 v34, s8, v132
	v_and_or_b32 v29, v29, s22, v31
	v_and_or_b32 v28, v28, s22, v30
	v_and_or_b32 v27, v36, s22, v27
	v_and_or_b32 v26, v37, s22, v26
	v_ashrrev_i32_e32 v35, 31, v34
	global_store_dwordx4 v[42:43], v[26:29], off offset:1024
	s_and_b64 vcc, exec, s[0:1]
	s_nop 0
	v_lshlrev_b64 v[26:27], 11, v[34:35]
	v_lshl_add_u64 v[36:37], s[6:7], 0, v[26:27]
	s_cbranch_vccnz .LBB0_823
	v_lshl_add_u64 v[26:27], v[36:37], 0, v[74:75]
	global_load_dwordx4 v[30:33], v[26:27], off nt
	s_cbranch_execz .LBB0_824

.LBB0_827:
	v_lshlrev_b32_e32 v36, 16, v22
	v_mul_f32_e32 v37, 0xbfb8aa3b, v36
	v_and_b32_e32 v22, 0xffff0000, v22
	v_exp_f32_e32 v38, v37
	v_lshlrev_b32_e32 v37, 16, v23
	v_mul_f32_e32 v39, 0xbfb8aa3b, v22
	v_exp_f32_e32 v39, v39
	v_mul_f32_e32 v40, 0xbfb8aa3b, v37
	v_exp_f32_e32 v41, v40
	v_and_b32_e32 v23, 0xffff0000, v23
	v_add_f32_e32 v39, 1.0, v39
	v_add_f32_e32 v38, 1.0, v38
	v_rcp_f32_e32 v40, v39
	v_add_f32_e32 v39, 1.0, v41
	v_mul_f32_e32 v41, 0xbfb8aa3b, v23
	v_rcp_f32_e32 v38, v38
	v_rcp_f32_e32 v39, v39
	v_exp_f32_e32 v41, v41
	s_waitcnt vmcnt(0) lgkmcnt(0)
	v_lshlrev_b32_e32 v43, 16, v31
	v_lshlrev_b32_e32 v42, 16, v30
	v_pk_mul_f32 v[36:37], v[38:39], v[36:37]
	v_add_f32_e32 v38, 1.0, v41
	v_rcp_f32_e32 v41, v38
	v_and_b32_e32 v31, 0xffff0000, v31
	v_and_b32_e32 v30, 0xffff0000, v30
	v_pk_mul_f32 v[36:37], v[36:37], v[42:43]
	v_pk_mul_f32 v[22:23], v[40:41], v[22:23]
	v_lshlrev_b32_e32 v45, 16, v33
	v_pk_mul_f32 v[22:23], v[22:23], v[30:31]
	v_lshlrev_b32_e32 v30, 16, v24
	v_mul_f32_e32 v31, 0xbfb8aa3b, v30
	v_and_b32_e32 v24, 0xffff0000, v24
	v_exp_f32_e32 v40, v31
	v_lshlrev_b32_e32 v31, 16, v25
	v_mul_f32_e32 v41, 0xbfb8aa3b, v24
	v_exp_f32_e32 v41, v41
	v_mul_f32_e32 v42, 0xbfb8aa3b, v31
	v_exp_f32_e32 v43, v42
	v_and_b32_e32 v25, 0xffff0000, v25
	v_add_f32_e32 v41, 1.0, v41
	v_add_f32_e32 v40, 1.0, v40
	v_rcp_f32_e32 v42, v41
	v_add_f32_e32 v41, 1.0, v43
	v_mul_f32_e32 v43, 0xbfb8aa3b, v25
	v_rcp_f32_e32 v40, v40
	v_rcp_f32_e32 v41, v41
	v_exp_f32_e32 v43, v43
	v_lshlrev_b32_e32 v44, 16, v32
	v_and_b32_e32 v33, 0xffff0000, v33
	v_pk_mul_f32 v[30:31], v[40:41], v[30:31]
	v_add_f32_e32 v40, 1.0, v43
	v_rcp_f32_e32 v43, v40
	v_and_b32_e32 v32, 0xffff0000, v32
	v_pk_mul_f32 v[30:31], v[30:31], v[44:45]
	v_lshlrev_b32_e32 v47, 16, v27
	v_pk_mul_f32 v[24:25], v[42:43], v[24:25]
	v_lshlrev_b32_e32 v46, 16, v26
	v_pk_mul_f32 v[24:25], v[24:25], v[32:33]
	v_lshlrev_b32_e32 v32, 16, v18
	v_mul_f32_e32 v33, 0xbfb8aa3b, v32
	v_and_b32_e32 v18, 0xffff0000, v18
	v_exp_f32_e32 v42, v33
	v_lshlrev_b32_e32 v33, 16, v19
	v_mul_f32_e32 v43, 0xbfb8aa3b, v18
	v_exp_f32_e32 v43, v43
	v_mul_f32_e32 v44, 0xbfb8aa3b, v33
	v_exp_f32_e32 v45, v44
	v_and_b32_e32 v19, 0xffff0000, v19
	v_add_f32_e32 v43, 1.0, v43
	v_add_f32_e32 v42, 1.0, v42
	v_rcp_f32_e32 v44, v43
	v_add_f32_e32 v43, 1.0, v45
	v_mul_f32_e32 v45, 0xbfb8aa3b, v19
	v_rcp_f32_e32 v42, v42
	v_rcp_f32_e32 v43, v43
	v_exp_f32_e32 v45, v45
	v_and_b32_e32 v27, 0xffff0000, v27
	v_and_b32_e32 v26, 0xffff0000, v26
	v_pk_mul_f32 v[32:33], v[42:43], v[32:33]
	v_add_f32_e32 v42, 1.0, v45
	v_rcp_f32_e32 v45, v42
	v_pk_mul_f32 v[32:33], v[32:33], v[46:47]
	v_pk_mul_f32 v[38:39], v[22:23], v[22:23]
	v_lshlrev_b32_e32 v49, 16, v29
	v_pk_mul_f32 v[18:19], v[44:45], v[18:19]
	v_lshlrev_b32_e32 v48, 16, v28
	v_pk_mul_f32 v[26:27], v[18:19], v[26:27]
	v_lshlrev_b32_e32 v18, 16, v20
	v_mul_f32_e32 v19, 0xbfb8aa3b, v18
	v_and_b32_e32 v20, 0xffff0000, v20
	v_exp_f32_e32 v44, v19
	v_lshlrev_b32_e32 v19, 16, v21
	v_mul_f32_e32 v45, 0xbfb8aa3b, v20
	v_exp_f32_e32 v45, v45
	v_mul_f32_e32 v46, 0xbfb8aa3b, v19
	v_exp_f32_e32 v47, v46
	v_and_b32_e32 v21, 0xffff0000, v21
	v_add_f32_e32 v45, 1.0, v45
	v_add_f32_e32 v44, 1.0, v44
	v_rcp_f32_e32 v46, v45
	v_add_f32_e32 v45, 1.0, v47
	v_mul_f32_e32 v47, 0xbfb8aa3b, v21
	v_rcp_f32_e32 v44, v44
	v_rcp_f32_e32 v45, v45
	v_exp_f32_e32 v47, v47
	v_pk_fma_f32 v[38:39], v[36:37], v[36:37], v[38:39]
	v_pk_mul_f32 v[40:41], v[24:25], v[24:25]
	v_pk_mul_f32 v[18:19], v[44:45], v[18:19]
	v_add_f32_e32 v44, 1.0, v47
	v_rcp_f32_e32 v47, v44
	v_pk_mul_f32 v[44:45], v[18:19], v[48:49]
	v_and_b32_e32 v19, 0xffff0000, v29
	v_and_b32_e32 v18, 0xffff0000, v28
	v_pk_mul_f32 v[20:21], v[46:47], v[20:21]
	v_pk_fma_f32 v[40:41], v[30:31], v[30:31], v[40:41]
	v_pk_mul_f32 v[28:29], v[20:21], v[18:19]
	v_add_f32_e32 v20, v38, v39
	v_pk_mul_f32 v[42:43], v[26:27], v[26:27]
	v_add_f32_e32 v20, v40, v20
	v_pk_fma_f32 v[42:43], v[32:33], v[32:33], v[42:43]
	v_add_f32_e32 v20, v41, v20
	v_pk_mul_f32 v[18:19], v[28:29], v[28:29]
	v_add_f32_e32 v20, v20, v42
	v_pk_fma_f32 v[18:19], v[44:45], v[44:45], v[18:19]
	v_add_f32_e32 v20, v43, v20
	v_add_f32_e32 v18, v18, v20
	v_add_f32_e32 v18, v19, v18
	s_mov_b64 s[16:17], -1
	s_nop 1
	v_add_f32_dpp v18, v18, v18 quad_perm:[1,0,3,2] row_mask:0xf bank_mask:0xf
	s_nop 1
	v_add_f32_dpp v18, v18, v18 quad_perm:[2,3,0,1] row_mask:0xf bank_mask:0xf
	s_nop 1
	v_add_f32_dpp v18, v18, v18 row_half_mirror row_mask:0xf bank_mask:0xf
	s_nop 1
	v_add_f32_dpp v18, v18, v18 row_mirror row_mask:0xf bank_mask:0xf
	s_nop 0
	v_readlane_b32 s98, v18, 0
	v_readlane_b32 s99, v18, 16
	v_readlane_b32 s100, v18, 32
	v_readlane_b32 s101, v18, 48
	v_mov_b32_e32 v19, s98
	v_add_f32_e32 v19, s99, v19
	v_add_f32_e32 v19, s100, v19
	v_add_f32_e32 v18, s101, v19
	s_waitcnt lgkmcnt(0)
	v_fmamk_f32 v18, v18, 0x3a800000, v138
	v_mul_f32_e32 v19, 0x4b800000, v18
	v_cmp_gt_f32_e32 vcc, s23, v18
	s_nop 1
	v_cndmask_b32_e32 v18, v18, v19, vcc
	v_rsq_f32_e32 v20, v18
	v_lshlrev_b64 v[18:19], 12, v[34:35]
	v_lshl_add_u64 v[18:19], s[10:11], 0, v[18:19]
	v_lshl_add_u64 v[34:35], v[18:19], 0, v[74:75]
	v_mul_f32_e32 v18, 0x45800000, v20
	v_cndmask_b32_e32 v38, v20, v18, vcc
	v_pk_mul_f32 v[20:21], v[22:23], v[38:39] op_sel_hi:[1,0]
	v_pk_mul_f32 v[24:25], v[24:25], v[38:39] op_sel_hi:[1,0]
	v_pk_mul_f32 v[18:19], v[36:37], v[38:39] op_sel_hi:[1,0]
	v_pk_mul_f32 v[22:23], v[30:31], v[38:39] op_sel_hi:[1,0]
	v_bfe_u32 v30, v25, 16, 1
	v_bfe_u32 v31, v24, 16, 1
	v_bfe_u32 v36, v21, 16, 1
	v_bfe_u32 v37, v20, 16, 1
	v_add3_u32 v37, v20, v37, s24
	v_add3_u32 v36, v21, v36, s24
	v_add3_u32 v20, v24, v31, s24
	v_add3_u32 v21, v25, v30, s24
	v_bfe_u32 v24, v18, 16, 1
	v_bfe_u32 v25, v19, 16, 1
	v_bfe_u32 v30, v22, 16, 1
	v_bfe_u32 v31, v23, 16, 1
	v_add3_u32 v23, v23, v31, s24
	v_add3_u32 v22, v22, v30, s24
	v_add3_u32 v19, v19, v25, s24
	v_add3_u32 v18, v18, v24, s24
	v_lshrrev_b32_e32 v18, 16, v18
	v_lshrrev_b32_e32 v19, 16, v19
	v_lshrrev_b32_e32 v22, 16, v22
	v_lshrrev_b32_e32 v23, 16, v23
	v_and_or_b32 v21, v21, s22, v23
	v_and_or_b32 v20, v20, s22, v22
	v_and_or_b32 v19, v36, s22, v19
	v_and_or_b32 v18, v37, s22, v18
	global_store_dwordx4 v[34:35], v[18:21], off
	v_pk_mul_f32 v[24:25], v[28:29], v[38:39] op_sel_hi:[1,0]
	v_pk_mul_f32 v[22:23], v[44:45], v[38:39] op_sel_hi:[1,0]
	v_pk_mul_f32 v[20:21], v[26:27], v[38:39] op_sel_hi:[1,0]
	v_pk_mul_f32 v[18:19], v[32:33], v[38:39] op_sel_hi:[1,0]
	v_bfe_u32 v26, v25, 16, 1
	v_bfe_u32 v27, v24, 16, 1
	v_bfe_u32 v28, v21, 16, 1
	v_bfe_u32 v29, v20, 16, 1
	v_add3_u32 v29, v20, v29, s24
	v_add3_u32 v28, v21, v28, s24
	v_add3_u32 v20, v24, v27, s24
	v_add3_u32 v21, v25, v26, s24
	v_bfe_u32 v24, v18, 16, 1
	v_bfe_u32 v25, v19, 16, 1
	v_bfe_u32 v26, v22, 16, 1
	v_bfe_u32 v27, v23, 16, 1
	v_add3_u32 v23, v23, v27, s24
	v_add3_u32 v22, v22, v26, s24
	v_add3_u32 v19, v19, v25, s24
	v_add3_u32 v18, v18, v24, s24
	v_lshrrev_b32_e32 v18, 16, v18
	v_lshrrev_b32_e32 v19, 16, v19
	v_lshrrev_b32_e32 v22, 16, v22
	v_lshrrev_b32_e32 v23, 16, v23
	v_add_u32_e32 v26, s8, v134
	v_and_or_b32 v21, v21, s22, v23
	v_and_or_b32 v20, v20, s22, v22
	v_and_or_b32 v19, v28, s22, v19
	v_and_or_b32 v18, v29, s22, v18
	v_ashrrev_i32_e32 v27, 31, v26
	global_store_dwordx4 v[34:35], v[18:21], off offset:1024
	s_and_b64 vcc, exec, s[0:1]
	s_nop 0
	v_lshlrev_b64 v[18:19], 11, v[26:27]
	v_lshl_add_u64 v[28:29], s[6:7], 0, v[18:19]
	s_cbranch_vccnz .LBB0_831
	v_lshl_add_u64 v[18:19], v[28:29], 0, v[74:75]
	global_load_dwordx4 v[22:25], v[18:19], off nt
	s_cbranch_execz .LBB0_832

.LBB0_835:
	v_lshlrev_b32_e32 v28, 16, v14
	v_mul_f32_e32 v29, 0xbfb8aa3b, v28
	v_and_b32_e32 v14, 0xffff0000, v14
	v_exp_f32_e32 v30, v29
	v_lshlrev_b32_e32 v29, 16, v15
	v_mul_f32_e32 v31, 0xbfb8aa3b, v14
	v_exp_f32_e32 v31, v31
	v_mul_f32_e32 v32, 0xbfb8aa3b, v29
	v_exp_f32_e32 v33, v32
	v_and_b32_e32 v15, 0xffff0000, v15
	v_add_f32_e32 v31, 1.0, v31
	v_add_f32_e32 v30, 1.0, v30
	v_rcp_f32_e32 v32, v31
	v_add_f32_e32 v31, 1.0, v33
	v_mul_f32_e32 v33, 0xbfb8aa3b, v15
	v_rcp_f32_e32 v30, v30
	v_rcp_f32_e32 v31, v31
	v_exp_f32_e32 v33, v33
	s_waitcnt vmcnt(0) lgkmcnt(0)
	v_lshlrev_b32_e32 v35, 16, v23
	v_lshlrev_b32_e32 v34, 16, v22
	v_pk_mul_f32 v[28:29], v[30:31], v[28:29]
	v_add_f32_e32 v30, 1.0, v33
	v_rcp_f32_e32 v33, v30
	v_and_b32_e32 v23, 0xffff0000, v23
	v_and_b32_e32 v22, 0xffff0000, v22
	v_pk_mul_f32 v[28:29], v[28:29], v[34:35]
	v_pk_mul_f32 v[14:15], v[32:33], v[14:15]
	v_lshlrev_b32_e32 v37, 16, v25
	v_pk_mul_f32 v[14:15], v[14:15], v[22:23]
	v_lshlrev_b32_e32 v22, 16, v16
	v_mul_f32_e32 v23, 0xbfb8aa3b, v22
	v_and_b32_e32 v16, 0xffff0000, v16
	v_exp_f32_e32 v32, v23
	v_lshlrev_b32_e32 v23, 16, v17
	v_mul_f32_e32 v33, 0xbfb8aa3b, v16
	v_exp_f32_e32 v33, v33
	v_mul_f32_e32 v34, 0xbfb8aa3b, v23
	v_exp_f32_e32 v35, v34
	v_and_b32_e32 v17, 0xffff0000, v17
	v_add_f32_e32 v33, 1.0, v33
	v_add_f32_e32 v32, 1.0, v32
	v_rcp_f32_e32 v34, v33
	v_add_f32_e32 v33, 1.0, v35
	v_mul_f32_e32 v35, 0xbfb8aa3b, v17
	v_rcp_f32_e32 v32, v32
	v_rcp_f32_e32 v33, v33
	v_exp_f32_e32 v35, v35
	v_lshlrev_b32_e32 v36, 16, v24
	v_and_b32_e32 v25, 0xffff0000, v25
	v_pk_mul_f32 v[22:23], v[32:33], v[22:23]
	v_add_f32_e32 v32, 1.0, v35
	v_rcp_f32_e32 v35, v32
	v_and_b32_e32 v24, 0xffff0000, v24
	v_pk_mul_f32 v[22:23], v[22:23], v[36:37]
	v_lshlrev_b32_e32 v39, 16, v19
	v_pk_mul_f32 v[16:17], v[34:35], v[16:17]
	v_lshlrev_b32_e32 v38, 16, v18
	v_pk_mul_f32 v[16:17], v[16:17], v[24:25]
	v_lshlrev_b32_e32 v24, 16, v10
	v_mul_f32_e32 v25, 0xbfb8aa3b, v24
	v_and_b32_e32 v10, 0xffff0000, v10
	v_exp_f32_e32 v34, v25
	v_lshlrev_b32_e32 v25, 16, v11
	v_mul_f32_e32 v35, 0xbfb8aa3b, v10
	v_exp_f32_e32 v35, v35
	v_mul_f32_e32 v36, 0xbfb8aa3b, v25
	v_exp_f32_e32 v37, v36
	v_and_b32_e32 v11, 0xffff0000, v11
	v_add_f32_e32 v35, 1.0, v35
	v_add_f32_e32 v34, 1.0, v34
	v_rcp_f32_e32 v36, v35
	v_add_f32_e32 v35, 1.0, v37
	v_mul_f32_e32 v37, 0xbfb8aa3b, v11
	v_rcp_f32_e32 v34, v34
	v_rcp_f32_e32 v35, v35
	v_exp_f32_e32 v37, v37
	v_and_b32_e32 v19, 0xffff0000, v19
	v_and_b32_e32 v18, 0xffff0000, v18
	v_pk_mul_f32 v[24:25], v[34:35], v[24:25]
	v_add_f32_e32 v34, 1.0, v37
	v_rcp_f32_e32 v37, v34
	v_pk_mul_f32 v[24:25], v[24:25], v[38:39]
	v_pk_mul_f32 v[30:31], v[14:15], v[14:15]
	v_lshlrev_b32_e32 v41, 16, v21
	v_pk_mul_f32 v[10:11], v[36:37], v[10:11]
	v_lshlrev_b32_e32 v40, 16, v20
	v_pk_mul_f32 v[18:19], v[10:11], v[18:19]
	v_lshlrev_b32_e32 v10, 16, v12
	v_mul_f32_e32 v11, 0xbfb8aa3b, v10
	v_and_b32_e32 v12, 0xffff0000, v12
	v_exp_f32_e32 v36, v11
	v_lshlrev_b32_e32 v11, 16, v13
	v_mul_f32_e32 v37, 0xbfb8aa3b, v12
	v_exp_f32_e32 v37, v37
	v_mul_f32_e32 v38, 0xbfb8aa3b, v11
	v_exp_f32_e32 v39, v38
	v_and_b32_e32 v13, 0xffff0000, v13
	v_add_f32_e32 v37, 1.0, v37
	v_add_f32_e32 v36, 1.0, v36
	v_rcp_f32_e32 v38, v37
	v_add_f32_e32 v37, 1.0, v39
	v_mul_f32_e32 v39, 0xbfb8aa3b, v13
	v_rcp_f32_e32 v36, v36
	v_rcp_f32_e32 v37, v37
	v_exp_f32_e32 v39, v39
	v_pk_fma_f32 v[30:31], v[28:29], v[28:29], v[30:31]
	v_pk_mul_f32 v[32:33], v[16:17], v[16:17]
	v_pk_mul_f32 v[10:11], v[36:37], v[10:11]
	v_add_f32_e32 v36, 1.0, v39
	v_rcp_f32_e32 v39, v36
	v_pk_mul_f32 v[36:37], v[10:11], v[40:41]
	v_and_b32_e32 v11, 0xffff0000, v21
	v_and_b32_e32 v10, 0xffff0000, v20
	v_pk_mul_f32 v[12:13], v[38:39], v[12:13]
	v_pk_fma_f32 v[32:33], v[22:23], v[22:23], v[32:33]
	v_pk_mul_f32 v[20:21], v[12:13], v[10:11]
	v_add_f32_e32 v12, v30, v31
	v_pk_mul_f32 v[34:35], v[18:19], v[18:19]
	v_add_f32_e32 v12, v32, v12
	v_pk_fma_f32 v[34:35], v[24:25], v[24:25], v[34:35]
	v_add_f32_e32 v12, v33, v12
	v_pk_mul_f32 v[10:11], v[20:21], v[20:21]
	v_add_f32_e32 v12, v12, v34
	v_pk_fma_f32 v[10:11], v[36:37], v[36:37], v[10:11]
	v_add_f32_e32 v12, v35, v12
	v_add_f32_e32 v10, v10, v12
	v_add_f32_e32 v10, v11, v10
	s_nop 1
	v_add_f32_dpp v10, v10, v10 quad_perm:[1,0,3,2] row_mask:0xf bank_mask:0xf
	s_nop 1
	v_add_f32_dpp v10, v10, v10 quad_perm:[2,3,0,1] row_mask:0xf bank_mask:0xf
	s_nop 1
	v_add_f32_dpp v10, v10, v10 row_half_mirror row_mask:0xf bank_mask:0xf
	s_nop 1
	v_add_f32_dpp v10, v10, v10 row_mirror row_mask:0xf bank_mask:0xf
	s_nop 0
	v_readlane_b32 s98, v10, 0
	v_readlane_b32 s99, v10, 16
	v_readlane_b32 s100, v10, 32
	v_readlane_b32 s101, v10, 48
	v_mov_b32_e32 v11, s98
	v_add_f32_e32 v11, s99, v11
	v_add_f32_e32 v11, s100, v11
	v_add_f32_e32 v10, s101, v11
	s_waitcnt lgkmcnt(0)
	v_fmamk_f32 v10, v10, 0x3a800000, v138
	v_mul_f32_e32 v11, 0x4b800000, v10
	v_cmp_gt_f32_e32 vcc, s23, v10
	s_nop 1
	v_cndmask_b32_e32 v10, v10, v11, vcc
	v_rsq_f32_e32 v12, v10
	v_lshlrev_b64 v[10:11], 12, v[26:27]
	v_lshl_add_u64 v[10:11], s[10:11], 0, v[10:11]
	v_lshl_add_u64 v[26:27], v[10:11], 0, v[74:75]
	v_mul_f32_e32 v10, 0x45800000, v12
	v_cndmask_b32_e32 v30, v12, v10, vcc
	v_pk_mul_f32 v[12:13], v[14:15], v[30:31] op_sel_hi:[1,0]
	v_pk_mul_f32 v[16:17], v[16:17], v[30:31] op_sel_hi:[1,0]
	v_pk_mul_f32 v[10:11], v[28:29], v[30:31] op_sel_hi:[1,0]
	v_pk_mul_f32 v[14:15], v[22:23], v[30:31] op_sel_hi:[1,0]
	v_bfe_u32 v22, v17, 16, 1
	v_bfe_u32 v23, v16, 16, 1
	v_bfe_u32 v28, v13, 16, 1
	v_bfe_u32 v29, v12, 16, 1
	v_add3_u32 v29, v12, v29, s24
	v_add3_u32 v28, v13, v28, s24
	v_add3_u32 v12, v16, v23, s24
	v_add3_u32 v13, v17, v22, s24
	v_bfe_u32 v16, v10, 16, 1
	v_bfe_u32 v17, v11, 16, 1
	v_bfe_u32 v22, v14, 16, 1
	v_bfe_u32 v23, v15, 16, 1
	v_add3_u32 v15, v15, v23, s24
	v_add3_u32 v14, v14, v22, s24
	v_add3_u32 v11, v11, v17, s24
	v_add3_u32 v10, v10, v16, s24
	v_lshrrev_b32_e32 v10, 16, v10
	v_lshrrev_b32_e32 v11, 16, v11
	v_lshrrev_b32_e32 v14, 16, v14
	v_lshrrev_b32_e32 v15, 16, v15
	v_and_or_b32 v13, v13, s22, v15
	v_and_or_b32 v12, v12, s22, v14
	v_and_or_b32 v11, v28, s22, v11
	v_and_or_b32 v10, v29, s22, v10
	global_store_dwordx4 v[26:27], v[10:13], off
	v_pk_mul_f32 v[16:17], v[20:21], v[30:31] op_sel_hi:[1,0]
	v_pk_mul_f32 v[14:15], v[36:37], v[30:31] op_sel_hi:[1,0]
	v_pk_mul_f32 v[12:13], v[18:19], v[30:31] op_sel_hi:[1,0]
	v_pk_mul_f32 v[10:11], v[24:25], v[30:31] op_sel_hi:[1,0]
	v_bfe_u32 v18, v17, 16, 1
	v_bfe_u32 v19, v16, 16, 1
	v_bfe_u32 v20, v13, 16, 1
	v_bfe_u32 v21, v12, 16, 1
	v_add3_u32 v21, v12, v21, s24
	v_add3_u32 v20, v13, v20, s24
	v_add3_u32 v12, v16, v19, s24
	v_add3_u32 v13, v17, v18, s24
	v_bfe_u32 v16, v10, 16, 1
	v_bfe_u32 v17, v11, 16, 1
	v_bfe_u32 v18, v14, 16, 1
	v_bfe_u32 v19, v15, 16, 1
	v_add3_u32 v15, v15, v19, s24
	v_add3_u32 v14, v14, v18, s24
	v_add3_u32 v11, v11, v17, s24
	v_add3_u32 v10, v10, v16, s24
	v_lshrrev_b32_e32 v10, 16, v10
	v_lshrrev_b32_e32 v11, 16, v11
	v_lshrrev_b32_e32 v14, 16, v14
	v_lshrrev_b32_e32 v15, 16, v15
	v_add_u32_e32 v18, s8, v136
	v_and_or_b32 v13, v13, s22, v15
	v_and_or_b32 v12, v12, s22, v14
	v_and_or_b32 v11, v20, s22, v11
	v_and_or_b32 v10, v21, s22, v10
	v_ashrrev_i32_e32 v19, 31, v18
	global_store_dwordx4 v[26:27], v[10:13], off offset:1024
	s_and_b64 vcc, exec, s[0:1]
	s_mov_b64 s[8:9], -1
	v_lshlrev_b64 v[10:11], 11, v[18:19]
	v_lshl_add_u64 v[20:21], s[6:7], 0, v[10:11]
	s_cbranch_vccnz .LBB0_839
	v_lshl_add_u64 v[10:11], v[20:21], 0, v[74:75]
	global_load_dwordx4 v[14:17], v[10:11], off nt
	s_cbranch_execz .LBB0_840
